# v8 plus: LDS-DMA loads of load phases P1/P4/P5/P8 use scalar base + 32-bit lane offset (8 VALU 64-bit adds per K-loop trip removed)
# speedup vs baseline: 1.0028x; 1.0028x over previous
; #define PG8_STAGE(bufoff, gbase, voff) do { _Pragma("unroll") for (int _i = 0; _i < 2; ++_i) \
;         __builtin_amdgcn_global_load_lds((const unsigned*)((const char*)(gbase) + (voff)[_i]), (LAS unsigned*)(lds + (bufoff) + ldsw + _i * 8192), 16, 0, 0); } while (0)
; #define PG8_LDA(dst, b, h) do { _Pragma("unroll") for (int m = 0; m < 4; ++m) _Pragma("unroll") for (int k = 0; k < 2; ++k) dst[m][k] = *(const LAS bf16x8*)(lds + PG8_SA(b, h) + aoff + m * 2048 + k * 1024); } while (0)
; #define PG8_LDB(dst, b, h) do { _Pragma("unroll") for (int n = 0; n < 2; ++n) _Pragma("unroll") for (int k = 0; k < 2; ++k) dst[n][k] = *(const LAS bf16x8*)(lds + PG8_SB(b, h) + boff + n * 2048 + k * 1024); } while (0)
; #define PG8_MMA(ai, bj, At, Bt) do { __builtin_amdgcn_s_setprio(1); _Pragma("unroll") for (int m = 0; m < 4; ++m) _Pragma("unroll") for (int n = 0; n < 2; ++n) _Pragma("unroll") for (int k = 0; k < 2; ++k) \
;         acc[ai][bj][m][n] = __builtin_amdgcn_mfma_f32_16x16x32_bf16(Bt[n][k], At[m][k], acc[ai][bj][m][n], 0, 0, 0); __builtin_amdgcn_s_setprio(0); } while (0)
; #define PG8_WAIT_V(n) asm volatile("s_waitcnt vmcnt(" #n ")" ::: "memory")
; #define PG8_WAIT_L(n) asm volatile("s_waitcnt lgkmcnt(" #n ")" ::: "memory")
; template <class Epi, class Sched>
; __device__ __forceinline__ void gemm_phase(LAS unsigned char* lds, const Gemm g, const Sched& S, const Epi& E) {
;     ...
;         for (int t = 0; t < nt; t += 2) {
;             const bool last = (t == nt - 2);
;             const char* a1 = cA + (size_t)(t + 1) * kstep;
;             const char* a2 = last ? nA : cA + (size_t)(t + 2) * kstep; const char* b2 = last ? nB : cB + (size_t)(t + 2) * kstep;
;             const char* a3 = a2 + kstep; const char* b3 = b2 + kstep;
;             PG8_LDB(B0, 0, 0); PG8_SCHED; PG8_LDA(At, 0, 0); PG8_STAGE(PG8_SA(1, 1), a1 + hstep, voffA);
;             PG8_WAIT_L(8); PG8_BAR; PG8_WAIT_L(0); PG8_MMA(0, 0, At, B0); PG8_BAR; PG8_SCHED;
;             PG8_LDB(B1, 0, 1); PG8_STAGE(PG8_SB(0, 0), b2, voffB);
;             PG8_BAR; PG8_WAIT_L(0); PG8_MMA(0, 1, At, B1); PG8_BAR;
;             PG8_LDA(At, 0, 1); PG8_STAGE(PG8_SA(0, 0), a2, voffA);
;             PG8_BAR; PG8_WAIT_L(0); PG8_MMA(1, 0, At, B0); PG8_BAR; PG8_SCHED;
;             PG8_STAGE(PG8_SB(0, 1), b2 + hstep, voffB);
;             PG8_WAIT_V(6); PG8_BAR; PG8_MMA(1, 1, At, B1); PG8_BAR;
.LBB0_165:
	s_add_u32 s24, s38, 0xfffc0080
	s_addc_u32 s25, s39, -1
	s_add_i32 vcc_hi, 0, 0x10000
	v_add_u32_e32 v166, vcc_hi, v167
	s_cmp_eq_u32 s50, 12
	s_cselect_b32 s61, s34, s25
	s_cselect_b32 s60, s45, s24
	s_cselect_b32 s49, s43, s35
	s_cselect_b32 s48, s79, vcc_lo
	s_add_i32 m0, s93, 0xc000
	ds_read_b128 v[214:217], v169 offset:6144
	ds_read_b128 v[218:221], v169 offset:7168
	global_load_lds_dwordx4 v140, s[38:39]
	s_add_i32 m0, s93, 0xe000
	s_nop 0
	global_load_lds_dwordx4 v138, s[38:39]
	s_waitcnt lgkmcnt(8)
	s_barrier
	s_waitcnt lgkmcnt(0)
	s_setprio 1
	s_waitcnt lgkmcnt(0)
	v_mfma_f32_16x16x32_bf16 v[126:129], v[142:145], v[190:193], v[126:129]
	v_mfma_f32_16x16x32_bf16 v[126:129], v[162:165], v[194:197], v[126:129]
	v_mfma_f32_16x16x32_bf16 v[122:125], v[182:185], v[190:193], v[122:125]
	v_mfma_f32_16x16x32_bf16 v[122:125], v[186:189], v[194:197], v[122:125]
	v_mfma_f32_16x16x32_bf16 v[110:113], v[142:145], v[198:201], v[110:113]
	v_mfma_f32_16x16x32_bf16 v[110:113], v[162:165], v[202:205], v[110:113]
	v_mfma_f32_16x16x32_bf16 v[106:109], v[182:185], v[198:201], v[106:109]
	v_mfma_f32_16x16x32_bf16 v[106:109], v[186:189], v[202:205], v[106:109]
	v_mfma_f32_16x16x32_bf16 v[94:97], v[142:145], v[206:209], v[94:97]
	v_mfma_f32_16x16x32_bf16 v[94:97], v[162:165], v[210:213], v[94:97]
	v_mfma_f32_16x16x32_bf16 v[90:93], v[182:185], v[206:209], v[90:93]
	v_mfma_f32_16x16x32_bf16 v[90:93], v[186:189], v[210:213], v[90:93]
	v_mfma_f32_16x16x32_bf16 v[78:81], v[142:145], v[214:217], v[78:81]
	v_mfma_f32_16x16x32_bf16 v[78:81], v[162:165], v[218:221], v[78:81]
	v_mfma_f32_16x16x32_bf16 v[74:77], v[182:185], v[214:217], v[74:77]
	s_barrier
	v_mfma_f32_16x16x32_bf16 v[74:77], v[186:189], v[218:221], v[74:77]
	s_setprio 0
	s_add_i32 s51, 0, 0x14000
	s_add_i32 s24, vcc_hi, s86
	v_add_u32_e32 v166, s51, v167
	v_lshl_add_u64 v[238:239], s[48:49], 0, v[134:135]
	s_mov_b32 m0, s24
	ds_read_b128 v[222:225], v166
	ds_read_b128 v[226:229], v166 offset:1024
	ds_read_b128 v[230:233], v166 offset:2048
	ds_read_b128 v[234:237], v166 offset:3072
	global_load_lds_dwordx4 v[238:239], off
	v_lshl_add_u64 v[240:241], s[48:49], 0, v[130:131]
	s_add_i32 m0, s24, 0x2000
	s_nop 0
	global_load_lds_dwordx4 v[240:241], off
	s_barrier
	s_waitcnt lgkmcnt(0)
	s_setprio 1
	s_waitcnt lgkmcnt(0)
	v_mfma_f32_16x16x32_bf16 v[118:121], v[222:225], v[190:193], v[118:121]
	v_mfma_f32_16x16x32_bf16 v[118:121], v[226:229], v[194:197], v[118:121]
	v_mfma_f32_16x16x32_bf16 v[114:117], v[230:233], v[190:193], v[114:117]
	v_mfma_f32_16x16x32_bf16 v[114:117], v[234:237], v[194:197], v[114:117]
	v_mfma_f32_16x16x32_bf16 v[102:105], v[222:225], v[198:201], v[102:105]
	v_mfma_f32_16x16x32_bf16 v[102:105], v[226:229], v[202:205], v[102:105]
	v_mfma_f32_16x16x32_bf16 v[98:101], v[230:233], v[198:201], v[98:101]
	v_mfma_f32_16x16x32_bf16 v[98:101], v[234:237], v[202:205], v[98:101]
	v_mfma_f32_16x16x32_bf16 v[86:89], v[222:225], v[206:209], v[86:89]
	v_mfma_f32_16x16x32_bf16 v[86:89], v[226:229], v[210:213], v[86:89]
	v_mfma_f32_16x16x32_bf16 v[82:85], v[230:233], v[206:209], v[82:85]
	v_mfma_f32_16x16x32_bf16 v[82:85], v[234:237], v[210:213], v[82:85]
	v_mfma_f32_16x16x32_bf16 v[70:73], v[222:225], v[214:217], v[70:73]
	v_mfma_f32_16x16x32_bf16 v[70:73], v[226:229], v[218:221], v[70:73]
	v_mfma_f32_16x16x32_bf16 v[66:69], v[230:233], v[214:217], v[66:69]
	s_barrier
	v_mfma_f32_16x16x32_bf16 v[66:69], v[234:237], v[218:221], v[66:69]
	s_setprio 0
	s_mov_b32 m0, s93
	v_lshl_add_u64 v[242:243], s[60:61], 0, v[136:137]
	ds_read_b128 v[190:193], v169 offset:16384
	ds_read_b128 v[194:197], v169 offset:17408
	ds_read_b128 v[198:201], v169 offset:18432
	ds_read_b128 v[202:205], v169 offset:19456
	ds_read_b128 v[206:209], v169 offset:20480
	ds_read_b128 v[210:213], v169 offset:21504
	ds_read_b128 v[214:217], v169 offset:22528
	ds_read_b128 v[218:221], v169 offset:23552
	global_load_lds_dwordx4 v[242:243], off
	v_lshl_add_u64 v[244:245], s[60:61], 0, v[132:133]
	s_mov_b32 m0, s98
	s_nop 0
	global_load_lds_dwordx4 v[244:245], off
	s_waitcnt vmcnt(8)
	s_barrier
	s_waitcnt lgkmcnt(0)
	s_setprio 1
	s_waitcnt lgkmcnt(0)
	v_mfma_f32_16x16x32_bf16 v[62:65], v[142:145], v[190:193], v[62:65]
	v_mfma_f32_16x16x32_bf16 v[62:65], v[162:165], v[194:197], v[62:65]
	v_mfma_f32_16x16x32_bf16 v[58:61], v[182:185], v[190:193], v[58:61]
	v_mfma_f32_16x16x32_bf16 v[58:61], v[186:189], v[194:197], v[58:61]
	v_mfma_f32_16x16x32_bf16 v[46:49], v[142:145], v[198:201], v[46:49]
	v_mfma_f32_16x16x32_bf16 v[46:49], v[162:165], v[202:205], v[46:49]
	v_mfma_f32_16x16x32_bf16 v[42:45], v[182:185], v[198:201], v[42:45]
	v_mfma_f32_16x16x32_bf16 v[42:45], v[186:189], v[202:205], v[42:45]
	v_mfma_f32_16x16x32_bf16 v[30:33], v[142:145], v[206:209], v[30:33]
	v_mfma_f32_16x16x32_bf16 v[30:33], v[162:165], v[210:213], v[30:33]
	v_mfma_f32_16x16x32_bf16 v[26:29], v[182:185], v[206:209], v[26:29]
	v_mfma_f32_16x16x32_bf16 v[26:29], v[186:189], v[210:213], v[26:29]
	v_mfma_f32_16x16x32_bf16 v[14:17], v[142:145], v[214:217], v[14:17]
	v_mfma_f32_16x16x32_bf16 v[14:17], v[162:165], v[218:221], v[14:17]
	v_mfma_f32_16x16x32_bf16 v[10:13], v[182:185], v[214:217], v[10:13]
	s_barrier
	v_mfma_f32_16x16x32_bf16 v[10:13], v[186:189], v[218:221], v[10:13]
	s_setprio 0
	s_add_u32 s24, s48, 0x40000
	s_addc_u32 s25, s49, 0
	s_add_i32 s51, s51, s86
	s_mov_b32 m0, s51
	s_nop 0
	global_load_lds_dwordx4 v134, s[24:25]
	s_add_i32 m0, s51, 0x2000
	s_nop 0
	global_load_lds_dwordx4 v130, s[24:25]
	s_waitcnt vmcnt(6)
	s_barrier
; #define PG8_STAGE(bufoff, gbase, voff) do { _Pragma("unroll") for (int _i = 0; _i < 2; ++_i) \
;         __builtin_amdgcn_global_load_lds((const unsigned*)((const char*)(gbase) + (voff)[_i]), (LAS unsigned*)(lds + (bufoff) + ldsw + _i * 8192), 16, 0, 0); } while (0)
; #define PG8_LDA(dst, b, h) do { _Pragma("unroll") for (int m = 0; m < 4; ++m) _Pragma("unroll") for (int k = 0; k < 2; ++k) dst[m][k] = *(const LAS bf16x8*)(lds + PG8_SA(b, h) + aoff + m * 2048 + k * 1024); } while (0)
; #define PG8_LDB(dst, b, h) do { _Pragma("unroll") for (int n = 0; n < 2; ++n) _Pragma("unroll") for (int k = 0; k < 2; ++k) dst[n][k] = *(const LAS bf16x8*)(lds + PG8_SB(b, h) + boff + n * 2048 + k * 1024); } while (0)
; #define PG8_MMA(ai, bj, At, Bt) do { __builtin_amdgcn_s_setprio(1); _Pragma("unroll") for (int m = 0; m < 4; ++m) _Pragma("unroll") for (int n = 0; n < 2; ++n) _Pragma("unroll") for (int k = 0; k < 2; ++k) \
;         acc[ai][bj][m][n] = __builtin_amdgcn_mfma_f32_16x16x32_bf16(Bt[n][k], At[m][k], acc[ai][bj][m][n], 0, 0, 0); __builtin_amdgcn_s_setprio(0); } while (0)
; #define PG8_WAIT_V(n) asm volatile("s_waitcnt vmcnt(" #n ")" ::: "memory")
; #define PG8_WAIT_L(n) asm volatile("s_waitcnt lgkmcnt(" #n ")" ::: "memory")
; #define PG8_BAR __builtin_amdgcn_s_barrier()
; #define PG8_SCHED __builtin_amdgcn_sched_barrier(0)
; template <class Epi, class Sched>
; __device__ __forceinline__ void gemm_phase(LAS unsigned char* lds, const Gemm g, const Sched& S, const Epi& E) {
;     ...
;             PG8_WAIT_V(6); PG8_BAR; PG8_MMA(1, 1, At, B1); PG8_BAR;
;             PG8_LDB(B0, 1, 0); PG8_SCHED; PG8_LDA(At, 1, 0); PG8_STAGE(PG8_SA(0, 1), a2 + hstep, voffA);
;             PG8_WAIT_L(8); PG8_BAR; PG8_WAIT_L(0); PG8_MMA(0, 0, At, B0); PG8_BAR; PG8_SCHED;
;             PG8_LDB(B1, 1, 1); PG8_STAGE(PG8_SB(1, 0), b3, voffB);
;             PG8_BAR; PG8_WAIT_L(0); PG8_MMA(0, 1, At, B1); PG8_BAR;
	s_setprio 1
	v_add_u32_e32 v249, 0x18000, v167
	v_mfma_f32_16x16x32_bf16 v[54:57], v[222:225], v[190:193], v[54:57]
	ds_read_b128 v[142:145], v249
	ds_read_b128 v[162:165], v249 offset:1024
	v_mfma_f32_16x16x32_bf16 v[54:57], v[226:229], v[194:197], v[54:57]
	ds_read_b128 v[182:185], v249 offset:2048
	ds_read_b128 v[186:189], v249 offset:3072
	v_mfma_f32_16x16x32_bf16 v[50:53], v[230:233], v[190:193], v[50:53]
	ds_read_b128 v[190:193], v169 offset:32768
	v_mfma_f32_16x16x32_bf16 v[50:53], v[234:237], v[194:197], v[50:53]
	ds_read_b128 v[194:197], v169 offset:33792
	v_mfma_f32_16x16x32_bf16 v[38:41], v[222:225], v[198:201], v[38:41]
	v_mfma_f32_16x16x32_bf16 v[38:41], v[226:229], v[202:205], v[38:41]
	v_mfma_f32_16x16x32_bf16 v[34:37], v[230:233], v[198:201], v[34:37]
	ds_read_b128 v[198:201], v169 offset:34816
	v_mfma_f32_16x16x32_bf16 v[34:37], v[234:237], v[202:205], v[34:37]
	ds_read_b128 v[202:205], v169 offset:35840
	v_mfma_f32_16x16x32_bf16 v[22:25], v[222:225], v[206:209], v[22:25]
	v_mfma_f32_16x16x32_bf16 v[22:25], v[226:229], v[210:213], v[22:25]
	v_mfma_f32_16x16x32_bf16 v[18:21], v[230:233], v[206:209], v[18:21]
	ds_read_b128 v[206:209], v169 offset:36864
	v_mfma_f32_16x16x32_bf16 v[18:21], v[234:237], v[210:213], v[18:21]
	ds_read_b128 v[210:213], v169 offset:37888
	v_mfma_f32_16x16x32_bf16 v[6:9], v[222:225], v[214:217], v[6:9]
	v_mfma_f32_16x16x32_bf16 v[6:9], v[226:229], v[218:221], v[6:9]
	v_mfma_f32_16x16x32_bf16 v[2:5], v[230:233], v[214:217], v[2:5]
	s_barrier
	v_mfma_f32_16x16x32_bf16 v[2:5], v[234:237], v[218:221], v[2:5]
	s_setprio 0
	s_add_i32 s51, 0, 0x18000
	v_add_u32_e32 v166, s51, v167
	s_add_u32 s24, s60, 0x40000
	s_addc_u32 s25, s61, 0
	s_mov_b32 m0, s99
	ds_read_b128 v[214:217], v169 offset:38912
	ds_read_b128 v[218:221], v169 offset:39936
	global_load_lds_dwordx4 v136, s[24:25]
	s_mov_b32 m0, s94
	s_nop 0
	global_load_lds_dwordx4 v132, s[24:25]
	s_waitcnt lgkmcnt(8)
	s_barrier
	s_waitcnt lgkmcnt(0)
	s_setprio 1
	s_waitcnt lgkmcnt(0)
	v_mfma_f32_16x16x32_bf16 v[126:129], v[142:145], v[190:193], v[126:129]
	v_mfma_f32_16x16x32_bf16 v[126:129], v[162:165], v[194:197], v[126:129]
	v_mfma_f32_16x16x32_bf16 v[122:125], v[182:185], v[190:193], v[122:125]
	v_mfma_f32_16x16x32_bf16 v[122:125], v[186:189], v[194:197], v[122:125]
	v_mfma_f32_16x16x32_bf16 v[110:113], v[142:145], v[198:201], v[110:113]
	v_mfma_f32_16x16x32_bf16 v[110:113], v[162:165], v[202:205], v[110:113]
	v_mfma_f32_16x16x32_bf16 v[106:109], v[182:185], v[198:201], v[106:109]
	v_mfma_f32_16x16x32_bf16 v[106:109], v[186:189], v[202:205], v[106:109]
	v_mfma_f32_16x16x32_bf16 v[94:97], v[142:145], v[206:209], v[94:97]
	v_mfma_f32_16x16x32_bf16 v[94:97], v[162:165], v[210:213], v[94:97]
	v_mfma_f32_16x16x32_bf16 v[90:93], v[182:185], v[206:209], v[90:93]
	v_mfma_f32_16x16x32_bf16 v[90:93], v[186:189], v[210:213], v[90:93]
	v_mfma_f32_16x16x32_bf16 v[78:81], v[142:145], v[214:217], v[78:81]
	v_mfma_f32_16x16x32_bf16 v[78:81], v[162:165], v[218:221], v[78:81]
	v_mfma_f32_16x16x32_bf16 v[74:77], v[182:185], v[214:217], v[74:77]
	s_barrier
	v_mfma_f32_16x16x32_bf16 v[74:77], v[186:189], v[218:221], v[74:77]
	s_setprio 0
	s_add_i32 s60, 0, 0x1c000
	s_add_i32 s24, s51, s86
	v_add_u32_e32 v166, s60, v167
	v_lshl_add_u64 v[238:239], v[238:239], 0, s[12:13]
	s_mov_b32 m0, s24
	ds_read_b128 v[222:225], v166
	ds_read_b128 v[226:229], v166 offset:1024
	ds_read_b128 v[230:233], v166 offset:2048
	ds_read_b128 v[234:237], v166 offset:3072
	global_load_lds_dwordx4 v[238:239], off
	v_lshl_add_u64 v[250:251], v[240:241], 0, s[12:13]
	s_add_i32 m0, s24, 0x2000
	s_nop 0
	global_load_lds_dwordx4 v[250:251], off
	s_barrier
	s_waitcnt lgkmcnt(0)
	s_setprio 1
	s_waitcnt lgkmcnt(0)
	v_mfma_f32_16x16x32_bf16 v[118:121], v[222:225], v[190:193], v[118:121]
	v_mfma_f32_16x16x32_bf16 v[118:121], v[226:229], v[194:197], v[118:121]
	v_mfma_f32_16x16x32_bf16 v[114:117], v[230:233], v[190:193], v[114:117]
	v_mfma_f32_16x16x32_bf16 v[114:117], v[234:237], v[194:197], v[114:117]
	v_mfma_f32_16x16x32_bf16 v[102:105], v[222:225], v[198:201], v[102:105]
	v_mfma_f32_16x16x32_bf16 v[102:105], v[226:229], v[202:205], v[102:105]
	v_mfma_f32_16x16x32_bf16 v[98:101], v[230:233], v[198:201], v[98:101]
	v_mfma_f32_16x16x32_bf16 v[98:101], v[234:237], v[202:205], v[98:101]
	v_mfma_f32_16x16x32_bf16 v[86:89], v[222:225], v[206:209], v[86:89]
	v_mfma_f32_16x16x32_bf16 v[86:89], v[226:229], v[210:213], v[86:89]
	v_mfma_f32_16x16x32_bf16 v[82:85], v[230:233], v[206:209], v[82:85]
	v_mfma_f32_16x16x32_bf16 v[82:85], v[234:237], v[210:213], v[82:85]
	v_mfma_f32_16x16x32_bf16 v[70:73], v[222:225], v[214:217], v[70:73]
	v_mfma_f32_16x16x32_bf16 v[70:73], v[226:229], v[218:221], v[70:73]
	v_mfma_f32_16x16x32_bf16 v[66:69], v[230:233], v[214:217], v[66:69]
	s_barrier
; #define PG8_STAGE(bufoff, gbase, voff) do { _Pragma("unroll") for (int _i = 0; _i < 2; ++_i) \
;         __builtin_amdgcn_global_load_lds((const unsigned*)((const char*)(gbase) + (voff)[_i]), (LAS unsigned*)(lds + (bufoff) + ldsw + _i * 8192), 16, 0, 0); } while (0)
; #define PG8_LDA(dst, b, h) do { _Pragma("unroll") for (int m = 0; m < 4; ++m) _Pragma("unroll") for (int k = 0; k < 2; ++k) dst[m][k] = *(const LAS bf16x8*)(lds + PG8_SA(b, h) + aoff + m * 2048 + k * 1024); } while (0)
; #define PG8_MMA(ai, bj, At, Bt) do { __builtin_amdgcn_s_setprio(1); _Pragma("unroll") for (int m = 0; m < 4; ++m) _Pragma("unroll") for (int n = 0; n < 2; ++n) _Pragma("unroll") for (int k = 0; k < 2; ++k) \
;         acc[ai][bj][m][n] = __builtin_amdgcn_mfma_f32_16x16x32_bf16(Bt[n][k], At[m][k], acc[ai][bj][m][n], 0, 0, 0); __builtin_amdgcn_s_setprio(0); } while (0)
; #define PG8_WAIT_V(n) asm volatile("s_waitcnt vmcnt(" #n ")" ::: "memory")
; #define PG8_WAIT_L(n) asm volatile("s_waitcnt lgkmcnt(" #n ")" ::: "memory")
; #define PG8_BAR __builtin_amdgcn_s_barrier()
; #define PG8_SCHED __builtin_amdgcn_sched_barrier(0)
; template <class Epi, class Sched>
; __device__ __forceinline__ void gemm_phase(LAS unsigned char* lds, const Gemm g, const Sched& S, const Epi& E) {
;     ...
;             PG8_LDA(At, 1, 1); PG8_STAGE(PG8_SA(1, 0), a3, voffA);
;             PG8_BAR; PG8_WAIT_L(0); PG8_MMA(1, 0, At, B0); PG8_BAR; PG8_SCHED;
;             PG8_STAGE(PG8_SB(1, 1), b3 + hstep, voffB);
;             PG8_WAIT_V(6); PG8_BAR; PG8_MMA(1, 1, At, B1); PG8_BAR;
;         }
;         if (wr == 0) PG8_BAR;
	v_mfma_f32_16x16x32_bf16 v[66:69], v[234:237], v[218:221], v[66:69]
	s_setprio 0
	s_mov_b32 m0, s95
	v_lshl_add_u64 v[238:239], v[242:243], 0, s[12:13]
	ds_read_b128 v[190:193], v169 offset:49152
	ds_read_b128 v[194:197], v169 offset:50176
	ds_read_b128 v[198:201], v169 offset:51200
	ds_read_b128 v[202:205], v169 offset:52224
	ds_read_b128 v[206:209], v169 offset:53248
	ds_read_b128 v[210:213], v169 offset:54272
	ds_read_b128 v[214:217], v169 offset:55296
	ds_read_b128 v[218:221], v169 offset:56320
	global_load_lds_dwordx4 v[238:239], off
	v_lshl_add_u64 v[250:251], v[244:245], 0, s[12:13]
	s_mov_b32 m0, s96
	s_nop 0
	global_load_lds_dwordx4 v[250:251], off
	s_waitcnt vmcnt(8)
	s_barrier
	s_waitcnt lgkmcnt(0)
	s_setprio 1
	s_waitcnt lgkmcnt(0)
	v_mfma_f32_16x16x32_bf16 v[62:65], v[142:145], v[190:193], v[62:65]
	v_mfma_f32_16x16x32_bf16 v[62:65], v[162:165], v[194:197], v[62:65]
	v_mfma_f32_16x16x32_bf16 v[58:61], v[182:185], v[190:193], v[58:61]
	v_mfma_f32_16x16x32_bf16 v[58:61], v[186:189], v[194:197], v[58:61]
	v_mfma_f32_16x16x32_bf16 v[46:49], v[142:145], v[198:201], v[46:49]
	v_mfma_f32_16x16x32_bf16 v[46:49], v[162:165], v[202:205], v[46:49]
	v_mfma_f32_16x16x32_bf16 v[42:45], v[182:185], v[198:201], v[42:45]
	v_mfma_f32_16x16x32_bf16 v[42:45], v[186:189], v[202:205], v[42:45]
	v_mfma_f32_16x16x32_bf16 v[30:33], v[142:145], v[206:209], v[30:33]
	v_mfma_f32_16x16x32_bf16 v[30:33], v[162:165], v[210:213], v[30:33]
	v_mfma_f32_16x16x32_bf16 v[26:29], v[182:185], v[206:209], v[26:29]
	v_mfma_f32_16x16x32_bf16 v[26:29], v[186:189], v[210:213], v[26:29]
	v_mfma_f32_16x16x32_bf16 v[14:17], v[142:145], v[214:217], v[14:17]
	v_mfma_f32_16x16x32_bf16 v[14:17], v[162:165], v[218:221], v[14:17]
	v_mfma_f32_16x16x32_bf16 v[10:13], v[182:185], v[214:217], v[10:13]
	s_barrier
	v_mfma_f32_16x16x32_bf16 v[10:13], v[186:189], v[218:221], v[10:13]
	s_setprio 0
	s_add_u32 s24, s48, 0x40080
	s_addc_u32 s25, s49, 0
	s_add_i32 s48, s60, s86
	s_mov_b32 m0, s48
	s_nop 0
	global_load_lds_dwordx4 v134, s[24:25]
	s_add_i32 m0, s48, 0x2000
	s_nop 0
	global_load_lds_dwordx4 v130, s[24:25]
	s_waitcnt vmcnt(6)
	s_barrier
	s_setprio 1
	v_add_u32_e32 v249, 0x10000, v167
	v_mfma_f32_16x16x32_bf16 v[54:57], v[222:225], v[190:193], v[54:57]
	ds_read_b128 v[142:145], v249
	ds_read_b128 v[162:165], v249 offset:1024
	v_mfma_f32_16x16x32_bf16 v[54:57], v[226:229], v[194:197], v[54:57]
	ds_read_b128 v[182:185], v249 offset:2048
	ds_read_b128 v[186:189], v249 offset:3072
	v_mfma_f32_16x16x32_bf16 v[50:53], v[230:233], v[190:193], v[50:53]
	ds_read_b128 v[190:193], v169
	v_mfma_f32_16x16x32_bf16 v[50:53], v[234:237], v[194:197], v[50:53]
	ds_read_b128 v[194:197], v169 offset:1024
	v_mfma_f32_16x16x32_bf16 v[38:41], v[222:225], v[198:201], v[38:41]
	v_mfma_f32_16x16x32_bf16 v[38:41], v[226:229], v[202:205], v[38:41]
	v_mfma_f32_16x16x32_bf16 v[34:37], v[230:233], v[198:201], v[34:37]
	ds_read_b128 v[198:201], v169 offset:2048
	v_mfma_f32_16x16x32_bf16 v[34:37], v[234:237], v[202:205], v[34:37]
	ds_read_b128 v[202:205], v169 offset:3072
	v_mfma_f32_16x16x32_bf16 v[22:25], v[222:225], v[206:209], v[22:25]
	v_mfma_f32_16x16x32_bf16 v[22:25], v[226:229], v[210:213], v[22:25]
	v_mfma_f32_16x16x32_bf16 v[18:21], v[230:233], v[206:209], v[18:21]
	ds_read_b128 v[206:209], v169 offset:4096
	v_mfma_f32_16x16x32_bf16 v[18:21], v[234:237], v[210:213], v[18:21]
	ds_read_b128 v[210:213], v169 offset:5120
	v_mfma_f32_16x16x32_bf16 v[6:9], v[222:225], v[214:217], v[6:9]
	v_mfma_f32_16x16x32_bf16 v[6:9], v[226:229], v[218:221], v[6:9]
	v_mfma_f32_16x16x32_bf16 v[2:5], v[230:233], v[214:217], v[2:5]
	s_barrier
	v_mfma_f32_16x16x32_bf16 v[2:5], v[234:237], v[218:221], v[2:5]
	s_setprio 0
	s_add_i32 s50, s50, 2
	s_add_u32 vcc_lo, vcc_lo, 0x100
	s_addc_u32 s35, s35, 0
	s_add_u32 s38, s38, 0x100
	s_addc_u32 s39, s39, 0
	s_cmp_gt_u32 s50, 13
	s_cbranch_scc0 .LBB0_165
	s_waitcnt lgkmcnt(0)
	s_and_b64 vcc, exec, s[40:41]
	s_cbranch_vccz .LBB0_168
	s_barrier

; #define PG8_STAGE(bufoff, gbase, voff) do { _Pragma("unroll") for (int _i = 0; _i < 2; ++_i) \
;         __builtin_amdgcn_global_load_lds((const unsigned*)((const char*)(gbase) + (voff)[_i]), (LAS unsigned*)(lds + (bufoff) + ldsw + _i * 8192), 16, 0, 0); } while (0)
; #define PG8_LDA(dst, b, h) do { _Pragma("unroll") for (int m = 0; m < 4; ++m) _Pragma("unroll") for (int k = 0; k < 2; ++k) dst[m][k] = *(const LAS bf16x8*)(lds + PG8_SA(b, h) + aoff + m * 2048 + k * 1024); } while (0)
; #define PG8_LDB(dst, b, h) do { _Pragma("unroll") for (int n = 0; n < 2; ++n) _Pragma("unroll") for (int k = 0; k < 2; ++k) dst[n][k] = *(const LAS bf16x8*)(lds + PG8_SB(b, h) + boff + n * 2048 + k * 1024); } while (0)
; #define PG8_MMA(ai, bj, At, Bt) do { __builtin_amdgcn_s_setprio(1); _Pragma("unroll") for (int m = 0; m < 4; ++m) _Pragma("unroll") for (int n = 0; n < 2; ++n) _Pragma("unroll") for (int k = 0; k < 2; ++k) \
;         acc[ai][bj][m][n] = __builtin_amdgcn_mfma_f32_16x16x32_bf16(Bt[n][k], At[m][k], acc[ai][bj][m][n], 0, 0, 0); __builtin_amdgcn_s_setprio(0); } while (0)
; #define PG8_WAIT_V(n) asm volatile("s_waitcnt vmcnt(" #n ")" ::: "memory")
; #define PG8_WAIT_L(n) asm volatile("s_waitcnt lgkmcnt(" #n ")" ::: "memory")
; template <class Epi, class Sched>
; __device__ __forceinline__ void gemm_phase(LAS unsigned char* lds, const Gemm g, const Sched& S, const Epi& E) {
;     ...
;         for (int t = 0; t < nt; t += 2) {
;             const bool last = (t == nt - 2);
;             const char* a1 = cA + (size_t)(t + 1) * kstep;
;             const char* a2 = last ? nA : cA + (size_t)(t + 2) * kstep; const char* b2 = last ? nB : cB + (size_t)(t + 2) * kstep;
;             const char* a3 = a2 + kstep; const char* b3 = b2 + kstep;
;             PG8_LDB(B0, 0, 0); PG8_SCHED; PG8_LDA(At, 0, 0); PG8_STAGE(PG8_SA(1, 1), a1 + hstep, voffA);
;             PG8_WAIT_L(8); PG8_BAR; PG8_WAIT_L(0); PG8_MMA(0, 0, At, B0); PG8_BAR; PG8_SCHED;
;             PG8_LDB(B1, 0, 1); PG8_STAGE(PG8_SB(0, 0), b2, voffB);
;             PG8_BAR; PG8_WAIT_L(0); PG8_MMA(0, 1, At, B1); PG8_BAR;
;             PG8_LDA(At, 0, 1); PG8_STAGE(PG8_SA(0, 0), a2, voffA);
;             PG8_BAR; PG8_WAIT_L(0); PG8_MMA(1, 0, At, B0); PG8_BAR; PG8_SCHED;
;             PG8_STAGE(PG8_SB(0, 1), b2 + hstep, voffB);
;             PG8_WAIT_V(6); PG8_BAR; PG8_MMA(1, 1, At, B1); PG8_BAR;
.LBB0_416:
	s_add_u32 s24, s0, 0xfffc0080
	s_addc_u32 s25, s1, -1
	s_add_i32 s39, 0, 0x10000
	v_add_u32_e32 v142, s39, v144
	s_cmp_eq_u32 s38, 12
	s_cselect_b32 vcc_hi, s77, s25
	s_cselect_b32 vcc_lo, s76, s24
	s_cselect_b32 s37, s47, s50
	s_cselect_b32 s36, s61, s35
	s_add_i32 m0, s93, 0xc000
	ds_read_b128 v[218:221], v162 offset:6144
	ds_read_b128 v[222:225], v162 offset:7168
	global_load_lds_dwordx4 v140, s[0:1]
	s_add_i32 m0, s93, 0xe000
	s_nop 0
	global_load_lds_dwordx4 v138, s[0:1]
	s_waitcnt lgkmcnt(8)
	s_barrier
	s_waitcnt lgkmcnt(0)
	s_setprio 1
	s_waitcnt lgkmcnt(0)
	v_mfma_f32_16x16x32_bf16 v[126:129], v[164:167], v[194:197], v[126:129]
	v_mfma_f32_16x16x32_bf16 v[126:129], v[182:185], v[198:201], v[126:129]
	v_mfma_f32_16x16x32_bf16 v[122:125], v[186:189], v[194:197], v[122:125]
	v_mfma_f32_16x16x32_bf16 v[122:125], v[190:193], v[198:201], v[122:125]
	v_mfma_f32_16x16x32_bf16 v[118:121], v[164:167], v[202:205], v[118:121]
	v_mfma_f32_16x16x32_bf16 v[118:121], v[182:185], v[206:209], v[118:121]
	v_mfma_f32_16x16x32_bf16 v[110:113], v[186:189], v[202:205], v[110:113]
	v_mfma_f32_16x16x32_bf16 v[110:113], v[190:193], v[206:209], v[110:113]
	v_mfma_f32_16x16x32_bf16 v[102:105], v[164:167], v[210:213], v[102:105]
	v_mfma_f32_16x16x32_bf16 v[102:105], v[182:185], v[214:217], v[102:105]
	v_mfma_f32_16x16x32_bf16 v[94:97], v[186:189], v[210:213], v[94:97]
	v_mfma_f32_16x16x32_bf16 v[94:97], v[190:193], v[214:217], v[94:97]
	v_mfma_f32_16x16x32_bf16 v[86:89], v[164:167], v[218:221], v[86:89]
	v_mfma_f32_16x16x32_bf16 v[86:89], v[182:185], v[222:225], v[86:89]
	v_mfma_f32_16x16x32_bf16 v[78:81], v[186:189], v[218:221], v[78:81]
	s_barrier
	v_mfma_f32_16x16x32_bf16 v[78:81], v[190:193], v[222:225], v[78:81]
	s_setprio 0
	s_add_i32 s51, 0, 0x14000
	v_add_u32_e32 v142, s51, v144
	s_add_i32 s24, s39, s86
	ds_read_b128 v[226:229], v142
	ds_read_b128 v[230:233], v142 offset:1024
	ds_read_b128 v[234:237], v142 offset:2048
	ds_read_b128 v[238:241], v142 offset:3072
	v_lshl_add_u64 v[142:143], s[36:37], 0, v[134:135]
	s_mov_b32 m0, s24
	v_lshl_add_u64 v[168:169], s[36:37], 0, v[130:131]
	global_load_lds_dwordx4 v[142:143], off
	s_add_i32 m0, s24, 0x2000
	s_nop 0
	global_load_lds_dwordx4 v[168:169], off
	s_barrier
	s_waitcnt lgkmcnt(0)
	s_setprio 1
	s_waitcnt lgkmcnt(0)
	v_mfma_f32_16x16x32_bf16 v[114:117], v[226:229], v[194:197], v[114:117]
	v_mfma_f32_16x16x32_bf16 v[114:117], v[230:233], v[198:201], v[114:117]
	v_mfma_f32_16x16x32_bf16 v[106:109], v[234:237], v[194:197], v[106:109]
	v_mfma_f32_16x16x32_bf16 v[106:109], v[238:241], v[198:201], v[106:109]
	v_mfma_f32_16x16x32_bf16 v[98:101], v[226:229], v[202:205], v[98:101]
	v_mfma_f32_16x16x32_bf16 v[98:101], v[230:233], v[206:209], v[98:101]
	v_mfma_f32_16x16x32_bf16 v[90:93], v[234:237], v[202:205], v[90:93]
	v_mfma_f32_16x16x32_bf16 v[90:93], v[238:241], v[206:209], v[90:93]
	v_mfma_f32_16x16x32_bf16 v[82:85], v[226:229], v[210:213], v[82:85]
	v_mfma_f32_16x16x32_bf16 v[82:85], v[230:233], v[214:217], v[82:85]
	v_mfma_f32_16x16x32_bf16 v[74:77], v[234:237], v[210:213], v[74:77]
	v_mfma_f32_16x16x32_bf16 v[74:77], v[238:241], v[214:217], v[74:77]
	v_mfma_f32_16x16x32_bf16 v[70:73], v[226:229], v[218:221], v[70:73]
	v_mfma_f32_16x16x32_bf16 v[70:73], v[230:233], v[222:225], v[70:73]
	v_mfma_f32_16x16x32_bf16 v[66:69], v[234:237], v[218:221], v[66:69]
	s_barrier
	v_mfma_f32_16x16x32_bf16 v[66:69], v[238:241], v[222:225], v[66:69]
	s_setprio 0
	s_mov_b32 m0, s93
	v_lshl_add_u64 v[242:243], vcc, 0, v[136:137]
	ds_read_b128 v[194:197], v162 offset:16384
	ds_read_b128 v[198:201], v162 offset:17408
	ds_read_b128 v[202:205], v162 offset:18432
	ds_read_b128 v[206:209], v162 offset:19456
	ds_read_b128 v[210:213], v162 offset:20480
	ds_read_b128 v[214:217], v162 offset:21504
	ds_read_b128 v[218:221], v162 offset:22528
	ds_read_b128 v[222:225], v162 offset:23552
	global_load_lds_dwordx4 v[242:243], off
	v_lshl_add_u64 v[244:245], vcc, 0, v[132:133]
	s_mov_b32 m0, s94
	s_nop 0
	global_load_lds_dwordx4 v[244:245], off
	s_waitcnt vmcnt(8)
	s_barrier
	s_waitcnt lgkmcnt(0)
	s_setprio 1
	s_waitcnt lgkmcnt(0)
	v_mfma_f32_16x16x32_bf16 v[62:65], v[164:167], v[194:197], v[62:65]
	v_mfma_f32_16x16x32_bf16 v[62:65], v[182:185], v[198:201], v[62:65]
	v_mfma_f32_16x16x32_bf16 v[58:61], v[186:189], v[194:197], v[58:61]
	v_mfma_f32_16x16x32_bf16 v[58:61], v[190:193], v[198:201], v[58:61]
	v_mfma_f32_16x16x32_bf16 v[54:57], v[164:167], v[202:205], v[54:57]
	v_mfma_f32_16x16x32_bf16 v[54:57], v[182:185], v[206:209], v[54:57]
	v_mfma_f32_16x16x32_bf16 v[46:49], v[186:189], v[202:205], v[46:49]
	v_mfma_f32_16x16x32_bf16 v[46:49], v[190:193], v[206:209], v[46:49]
	v_mfma_f32_16x16x32_bf16 v[38:41], v[164:167], v[210:213], v[38:41]
	v_mfma_f32_16x16x32_bf16 v[38:41], v[182:185], v[214:217], v[38:41]
	v_mfma_f32_16x16x32_bf16 v[30:33], v[186:189], v[210:213], v[30:33]
	v_mfma_f32_16x16x32_bf16 v[30:33], v[190:193], v[214:217], v[30:33]
	v_mfma_f32_16x16x32_bf16 v[22:25], v[164:167], v[218:221], v[22:25]
	v_mfma_f32_16x16x32_bf16 v[22:25], v[182:185], v[222:225], v[22:25]
	v_mfma_f32_16x16x32_bf16 v[14:17], v[186:189], v[218:221], v[14:17]
	s_barrier
	v_mfma_f32_16x16x32_bf16 v[14:17], v[190:193], v[222:225], v[14:17]
	s_setprio 0
	s_add_u32 s24, s36, 0x40000
	s_addc_u32 s25, s37, 0
	s_add_i32 s39, s51, s86
	s_mov_b32 m0, s39
	s_nop 0
	global_load_lds_dwordx4 v134, s[24:25]
	s_add_i32 m0, s39, 0x2000
	s_nop 0
	global_load_lds_dwordx4 v130, s[24:25]
	s_waitcnt vmcnt(6)
	s_barrier
; #define PG8_STAGE(bufoff, gbase, voff) do { _Pragma("unroll") for (int _i = 0; _i < 2; ++_i) \
;         __builtin_amdgcn_global_load_lds((const unsigned*)((const char*)(gbase) + (voff)[_i]), (LAS unsigned*)(lds + (bufoff) + ldsw + _i * 8192), 16, 0, 0); } while (0)
; #define PG8_LDA(dst, b, h) do { _Pragma("unroll") for (int m = 0; m < 4; ++m) _Pragma("unroll") for (int k = 0; k < 2; ++k) dst[m][k] = *(const LAS bf16x8*)(lds + PG8_SA(b, h) + aoff + m * 2048 + k * 1024); } while (0)
; #define PG8_LDB(dst, b, h) do { _Pragma("unroll") for (int n = 0; n < 2; ++n) _Pragma("unroll") for (int k = 0; k < 2; ++k) dst[n][k] = *(const LAS bf16x8*)(lds + PG8_SB(b, h) + boff + n * 2048 + k * 1024); } while (0)
; #define PG8_MMA(ai, bj, At, Bt) do { __builtin_amdgcn_s_setprio(1); _Pragma("unroll") for (int m = 0; m < 4; ++m) _Pragma("unroll") for (int n = 0; n < 2; ++n) _Pragma("unroll") for (int k = 0; k < 2; ++k) \
;         acc[ai][bj][m][n] = __builtin_amdgcn_mfma_f32_16x16x32_bf16(Bt[n][k], At[m][k], acc[ai][bj][m][n], 0, 0, 0); __builtin_amdgcn_s_setprio(0); } while (0)
; #define PG8_WAIT_V(n) asm volatile("s_waitcnt vmcnt(" #n ")" ::: "memory")
; #define PG8_WAIT_L(n) asm volatile("s_waitcnt lgkmcnt(" #n ")" ::: "memory")
; #define PG8_BAR __builtin_amdgcn_s_barrier()
; #define PG8_SCHED __builtin_amdgcn_sched_barrier(0)
; template <class Epi, class Sched>
; __device__ __forceinline__ void gemm_phase(LAS unsigned char* lds, const Gemm g, const Sched& S, const Epi& E) {
;     ...
;             PG8_WAIT_V(6); PG8_BAR; PG8_MMA(1, 1, At, B1); PG8_BAR;
;             PG8_LDB(B0, 1, 0); PG8_SCHED; PG8_LDA(At, 1, 0); PG8_STAGE(PG8_SA(0, 1), a2 + hstep, voffA);
;             PG8_WAIT_L(8); PG8_BAR; PG8_WAIT_L(0); PG8_MMA(0, 0, At, B0); PG8_BAR; PG8_SCHED;
;             PG8_LDB(B1, 1, 1); PG8_STAGE(PG8_SB(1, 0), b3, voffB);
;             PG8_BAR; PG8_WAIT_L(0); PG8_MMA(0, 1, At, B1); PG8_BAR;
	s_setprio 1
	v_add_u32_e32 v249, 0x18000, v144
	v_mfma_f32_16x16x32_bf16 v[50:53], v[226:229], v[194:197], v[50:53]
	ds_read_b128 v[164:167], v249
	ds_read_b128 v[182:185], v249 offset:1024
	v_mfma_f32_16x16x32_bf16 v[50:53], v[230:233], v[198:201], v[50:53]
	ds_read_b128 v[186:189], v249 offset:2048
	ds_read_b128 v[190:193], v249 offset:3072
	v_mfma_f32_16x16x32_bf16 v[42:45], v[234:237], v[194:197], v[42:45]
	ds_read_b128 v[194:197], v162 offset:32768
	v_mfma_f32_16x16x32_bf16 v[42:45], v[238:241], v[198:201], v[42:45]
	ds_read_b128 v[198:201], v162 offset:33792
	v_mfma_f32_16x16x32_bf16 v[34:37], v[226:229], v[202:205], v[34:37]
	v_mfma_f32_16x16x32_bf16 v[34:37], v[230:233], v[206:209], v[34:37]
	v_mfma_f32_16x16x32_bf16 v[26:29], v[234:237], v[202:205], v[26:29]
	ds_read_b128 v[202:205], v162 offset:34816
	v_mfma_f32_16x16x32_bf16 v[26:29], v[238:241], v[206:209], v[26:29]
	ds_read_b128 v[206:209], v162 offset:35840
	v_mfma_f32_16x16x32_bf16 v[18:21], v[226:229], v[210:213], v[18:21]
	v_mfma_f32_16x16x32_bf16 v[18:21], v[230:233], v[214:217], v[18:21]
	v_mfma_f32_16x16x32_bf16 v[10:13], v[234:237], v[210:213], v[10:13]
	ds_read_b128 v[210:213], v162 offset:36864
	v_mfma_f32_16x16x32_bf16 v[10:13], v[238:241], v[214:217], v[10:13]
	ds_read_b128 v[214:217], v162 offset:37888
	v_mfma_f32_16x16x32_bf16 v[6:9], v[226:229], v[218:221], v[6:9]
	v_mfma_f32_16x16x32_bf16 v[6:9], v[230:233], v[222:225], v[6:9]
	v_mfma_f32_16x16x32_bf16 v[2:5], v[234:237], v[218:221], v[2:5]
	s_barrier
	v_mfma_f32_16x16x32_bf16 v[2:5], v[238:241], v[222:225], v[2:5]
	s_setprio 0
	s_add_i32 s39, 0, 0x18000
	v_add_u32_e32 v163, s39, v144
	s_add_u32 s24, vcc_lo, 0x40000
	s_addc_u32 s25, vcc_hi, 0
	s_mov_b32 m0, s95
	ds_read_b128 v[218:221], v162 offset:38912
	ds_read_b128 v[222:225], v162 offset:39936
	global_load_lds_dwordx4 v136, s[24:25]
	s_mov_b32 m0, s96
	s_nop 0
	global_load_lds_dwordx4 v132, s[24:25]
	s_waitcnt lgkmcnt(8)
	s_barrier
	s_waitcnt lgkmcnt(0)
	s_setprio 1
	s_waitcnt lgkmcnt(0)
	v_mfma_f32_16x16x32_bf16 v[126:129], v[164:167], v[194:197], v[126:129]
	v_mfma_f32_16x16x32_bf16 v[126:129], v[182:185], v[198:201], v[126:129]
	v_mfma_f32_16x16x32_bf16 v[122:125], v[186:189], v[194:197], v[122:125]
	v_mfma_f32_16x16x32_bf16 v[122:125], v[190:193], v[198:201], v[122:125]
	v_mfma_f32_16x16x32_bf16 v[118:121], v[164:167], v[202:205], v[118:121]
	v_mfma_f32_16x16x32_bf16 v[118:121], v[182:185], v[206:209], v[118:121]
	v_mfma_f32_16x16x32_bf16 v[110:113], v[186:189], v[202:205], v[110:113]
	v_mfma_f32_16x16x32_bf16 v[110:113], v[190:193], v[206:209], v[110:113]
	v_mfma_f32_16x16x32_bf16 v[102:105], v[164:167], v[210:213], v[102:105]
	v_mfma_f32_16x16x32_bf16 v[102:105], v[182:185], v[214:217], v[102:105]
	v_mfma_f32_16x16x32_bf16 v[94:97], v[186:189], v[210:213], v[94:97]
	v_mfma_f32_16x16x32_bf16 v[94:97], v[190:193], v[214:217], v[94:97]
	v_mfma_f32_16x16x32_bf16 v[86:89], v[164:167], v[218:221], v[86:89]
	v_mfma_f32_16x16x32_bf16 v[86:89], v[182:185], v[222:225], v[86:89]
	v_mfma_f32_16x16x32_bf16 v[78:81], v[186:189], v[218:221], v[78:81]
	s_barrier
	v_mfma_f32_16x16x32_bf16 v[78:81], v[190:193], v[222:225], v[78:81]
	s_setprio 0
	s_add_i32 s51, 0, 0x1c000
	s_add_i32 s24, s39, s86
	v_add_u32_e32 v163, s51, v144
	v_lshl_add_u64 v[142:143], v[142:143], 0, s[12:13]
	s_mov_b32 m0, s24
	ds_read_b128 v[226:229], v163
	ds_read_b128 v[230:233], v163 offset:1024
	ds_read_b128 v[234:237], v163 offset:2048
	ds_read_b128 v[238:241], v163 offset:3072
	global_load_lds_dwordx4 v[142:143], off
	v_lshl_add_u64 v[250:251], v[168:169], 0, s[12:13]
	s_add_i32 m0, s24, 0x2000
	s_nop 0
	global_load_lds_dwordx4 v[250:251], off
	s_barrier
	s_waitcnt lgkmcnt(0)
	s_setprio 1
	s_waitcnt lgkmcnt(0)
	v_mfma_f32_16x16x32_bf16 v[114:117], v[226:229], v[194:197], v[114:117]
	v_mfma_f32_16x16x32_bf16 v[114:117], v[230:233], v[198:201], v[114:117]
	v_mfma_f32_16x16x32_bf16 v[106:109], v[234:237], v[194:197], v[106:109]
	v_mfma_f32_16x16x32_bf16 v[106:109], v[238:241], v[198:201], v[106:109]
	v_mfma_f32_16x16x32_bf16 v[98:101], v[226:229], v[202:205], v[98:101]
	v_mfma_f32_16x16x32_bf16 v[98:101], v[230:233], v[206:209], v[98:101]
	v_mfma_f32_16x16x32_bf16 v[90:93], v[234:237], v[202:205], v[90:93]
	v_mfma_f32_16x16x32_bf16 v[90:93], v[238:241], v[206:209], v[90:93]
	v_mfma_f32_16x16x32_bf16 v[82:85], v[226:229], v[210:213], v[82:85]
	v_mfma_f32_16x16x32_bf16 v[82:85], v[230:233], v[214:217], v[82:85]
	v_mfma_f32_16x16x32_bf16 v[74:77], v[234:237], v[210:213], v[74:77]
	v_mfma_f32_16x16x32_bf16 v[74:77], v[238:241], v[214:217], v[74:77]
	v_mfma_f32_16x16x32_bf16 v[70:73], v[226:229], v[218:221], v[70:73]
	v_mfma_f32_16x16x32_bf16 v[70:73], v[230:233], v[222:225], v[70:73]
	v_mfma_f32_16x16x32_bf16 v[66:69], v[234:237], v[218:221], v[66:69]
	s_barrier
; #define PG8_STAGE(bufoff, gbase, voff) do { _Pragma("unroll") for (int _i = 0; _i < 2; ++_i) \
;         __builtin_amdgcn_global_load_lds((const unsigned*)((const char*)(gbase) + (voff)[_i]), (LAS unsigned*)(lds + (bufoff) + ldsw + _i * 8192), 16, 0, 0); } while (0)
; #define PG8_LDA(dst, b, h) do { _Pragma("unroll") for (int m = 0; m < 4; ++m) _Pragma("unroll") for (int k = 0; k < 2; ++k) dst[m][k] = *(const LAS bf16x8*)(lds + PG8_SA(b, h) + aoff + m * 2048 + k * 1024); } while (0)
; #define PG8_MMA(ai, bj, At, Bt) do { __builtin_amdgcn_s_setprio(1); _Pragma("unroll") for (int m = 0; m < 4; ++m) _Pragma("unroll") for (int n = 0; n < 2; ++n) _Pragma("unroll") for (int k = 0; k < 2; ++k) \
;         acc[ai][bj][m][n] = __builtin_amdgcn_mfma_f32_16x16x32_bf16(Bt[n][k], At[m][k], acc[ai][bj][m][n], 0, 0, 0); __builtin_amdgcn_s_setprio(0); } while (0)
; #define PG8_WAIT_V(n) asm volatile("s_waitcnt vmcnt(" #n ")" ::: "memory")
; #define PG8_WAIT_L(n) asm volatile("s_waitcnt lgkmcnt(" #n ")" ::: "memory")
; #define PG8_BAR __builtin_amdgcn_s_barrier()
; #define PG8_SCHED __builtin_amdgcn_sched_barrier(0)
; template <class Epi, class Sched>
; __device__ __forceinline__ void gemm_phase(LAS unsigned char* lds, const Gemm g, const Sched& S, const Epi& E) {
;     ...
;             PG8_BAR; PG8_WAIT_L(0); PG8_MMA(0, 1, At, B1); PG8_BAR;
;             PG8_LDA(At, 1, 1); PG8_STAGE(PG8_SA(1, 0), a3, voffA);
;             PG8_BAR; PG8_WAIT_L(0); PG8_MMA(1, 0, At, B0); PG8_BAR; PG8_SCHED;
;             PG8_STAGE(PG8_SB(1, 1), b3 + hstep, voffB);
;             PG8_WAIT_V(6); PG8_BAR; PG8_MMA(1, 1, At, B1); PG8_BAR;
	v_mfma_f32_16x16x32_bf16 v[66:69], v[238:241], v[222:225], v[66:69]
	s_setprio 0
	s_mov_b32 m0, s97
	v_lshl_add_u64 v[142:143], v[242:243], 0, s[12:13]
	ds_read_b128 v[194:197], v162 offset:49152
	ds_read_b128 v[198:201], v162 offset:50176
	ds_read_b128 v[202:205], v162 offset:51200
	ds_read_b128 v[206:209], v162 offset:52224
	ds_read_b128 v[210:213], v162 offset:53248
	ds_read_b128 v[214:217], v162 offset:54272
	ds_read_b128 v[218:221], v162 offset:55296
	ds_read_b128 v[222:225], v162 offset:56320
	global_load_lds_dwordx4 v[142:143], off
	v_lshl_add_u64 v[250:251], v[244:245], 0, s[12:13]
	s_mov_b32 m0, s98
	s_nop 0
	global_load_lds_dwordx4 v[250:251], off
	s_waitcnt vmcnt(8)
	s_barrier
	s_waitcnt lgkmcnt(0)
	s_setprio 1
	s_waitcnt lgkmcnt(0)
	v_mfma_f32_16x16x32_bf16 v[62:65], v[164:167], v[194:197], v[62:65]
	v_mfma_f32_16x16x32_bf16 v[62:65], v[182:185], v[198:201], v[62:65]
	v_mfma_f32_16x16x32_bf16 v[58:61], v[186:189], v[194:197], v[58:61]
	v_mfma_f32_16x16x32_bf16 v[58:61], v[190:193], v[198:201], v[58:61]
	v_mfma_f32_16x16x32_bf16 v[54:57], v[164:167], v[202:205], v[54:57]
	v_mfma_f32_16x16x32_bf16 v[54:57], v[182:185], v[206:209], v[54:57]
	v_mfma_f32_16x16x32_bf16 v[46:49], v[186:189], v[202:205], v[46:49]
	v_mfma_f32_16x16x32_bf16 v[46:49], v[190:193], v[206:209], v[46:49]
	v_mfma_f32_16x16x32_bf16 v[38:41], v[164:167], v[210:213], v[38:41]
	v_mfma_f32_16x16x32_bf16 v[38:41], v[182:185], v[214:217], v[38:41]
	v_mfma_f32_16x16x32_bf16 v[30:33], v[186:189], v[210:213], v[30:33]
	v_mfma_f32_16x16x32_bf16 v[30:33], v[190:193], v[214:217], v[30:33]
	v_mfma_f32_16x16x32_bf16 v[22:25], v[164:167], v[218:221], v[22:25]
	v_mfma_f32_16x16x32_bf16 v[22:25], v[182:185], v[222:225], v[22:25]
	v_mfma_f32_16x16x32_bf16 v[14:17], v[186:189], v[218:221], v[14:17]
	s_barrier
	v_mfma_f32_16x16x32_bf16 v[14:17], v[190:193], v[222:225], v[14:17]
	s_setprio 0
	s_add_u32 s24, s36, 0x40080
	s_addc_u32 s25, s37, 0
	s_add_i32 s36, s51, s86
	s_mov_b32 m0, s36
	s_nop 0
	global_load_lds_dwordx4 v134, s[24:25]
	s_add_i32 m0, s36, 0x2000
	s_nop 0
	global_load_lds_dwordx4 v130, s[24:25]
	s_waitcnt vmcnt(6)
	s_barrier
	s_setprio 1
	v_add_u32_e32 v249, 0x10000, v144
	v_mfma_f32_16x16x32_bf16 v[50:53], v[226:229], v[194:197], v[50:53]
	ds_read_b128 v[164:167], v249
	ds_read_b128 v[182:185], v249 offset:1024
	v_mfma_f32_16x16x32_bf16 v[50:53], v[230:233], v[198:201], v[50:53]
	ds_read_b128 v[186:189], v249 offset:2048
	ds_read_b128 v[190:193], v249 offset:3072
	v_mfma_f32_16x16x32_bf16 v[42:45], v[234:237], v[194:197], v[42:45]
	ds_read_b128 v[194:197], v162
	v_mfma_f32_16x16x32_bf16 v[42:45], v[238:241], v[198:201], v[42:45]
	ds_read_b128 v[198:201], v162 offset:1024
	v_mfma_f32_16x16x32_bf16 v[34:37], v[226:229], v[202:205], v[34:37]
	v_mfma_f32_16x16x32_bf16 v[34:37], v[230:233], v[206:209], v[34:37]
	v_mfma_f32_16x16x32_bf16 v[26:29], v[234:237], v[202:205], v[26:29]
	ds_read_b128 v[202:205], v162 offset:2048
	v_mfma_f32_16x16x32_bf16 v[26:29], v[238:241], v[206:209], v[26:29]
	ds_read_b128 v[206:209], v162 offset:3072
	v_mfma_f32_16x16x32_bf16 v[18:21], v[226:229], v[210:213], v[18:21]
	v_mfma_f32_16x16x32_bf16 v[18:21], v[230:233], v[214:217], v[18:21]
	v_mfma_f32_16x16x32_bf16 v[10:13], v[234:237], v[210:213], v[10:13]
	ds_read_b128 v[210:213], v162 offset:4096
	v_mfma_f32_16x16x32_bf16 v[10:13], v[238:241], v[214:217], v[10:13]
	ds_read_b128 v[214:217], v162 offset:5120
	v_mfma_f32_16x16x32_bf16 v[6:9], v[226:229], v[218:221], v[6:9]
	v_mfma_f32_16x16x32_bf16 v[6:9], v[230:233], v[222:225], v[6:9]
	v_mfma_f32_16x16x32_bf16 v[2:5], v[234:237], v[218:221], v[2:5]
	s_barrier
	v_mfma_f32_16x16x32_bf16 v[2:5], v[238:241], v[222:225], v[2:5]
	s_setprio 0
	s_add_i32 s38, s38, 2
	s_add_u32 s35, s35, 0x100
	s_addc_u32 s50, s50, 0
	s_add_u32 s0, s0, 0x100
	s_addc_u32 s1, s1, 0
	s_cmp_gt_u32 s38, 13
	s_cbranch_scc0 .LBB0_416
	s_waitcnt lgkmcnt(0)
	s_and_b64 vcc, exec, s[44:45]
	s_cbranch_vccz .LBB0_419
	s_barrier

; #define PG8_STAGE(bufoff, gbase, voff) do { _Pragma("unroll") for (int _i = 0; _i < 2; ++_i) \
;         __builtin_amdgcn_global_load_lds((const unsigned*)((const char*)(gbase) + (voff)[_i]), (LAS unsigned*)(lds + (bufoff) + ldsw + _i * 8192), 16, 0, 0); } while (0)
; #define PG8_LDA(dst, b, h) do { _Pragma("unroll") for (int m = 0; m < 4; ++m) _Pragma("unroll") for (int k = 0; k < 2; ++k) dst[m][k] = *(const LAS bf16x8*)(lds + PG8_SA(b, h) + aoff + m * 2048 + k * 1024); } while (0)
; #define PG8_LDB(dst, b, h) do { _Pragma("unroll") for (int n = 0; n < 2; ++n) _Pragma("unroll") for (int k = 0; k < 2; ++k) dst[n][k] = *(const LAS bf16x8*)(lds + PG8_SB(b, h) + boff + n * 2048 + k * 1024); } while (0)
; #define PG8_MMA(ai, bj, At, Bt) do { __builtin_amdgcn_s_setprio(1); _Pragma("unroll") for (int m = 0; m < 4; ++m) _Pragma("unroll") for (int n = 0; n < 2; ++n) _Pragma("unroll") for (int k = 0; k < 2; ++k) \
;         acc[ai][bj][m][n] = __builtin_amdgcn_mfma_f32_16x16x32_bf16(Bt[n][k], At[m][k], acc[ai][bj][m][n], 0, 0, 0); __builtin_amdgcn_s_setprio(0); } while (0)
; #define PG8_WAIT_V(n) asm volatile("s_waitcnt vmcnt(" #n ")" ::: "memory")
; #define PG8_WAIT_L(n) asm volatile("s_waitcnt lgkmcnt(" #n ")" ::: "memory")
; #define PG8_BAR __builtin_amdgcn_s_barrier()
; template <class Epi, class Sched>
; __device__ __forceinline__ void gemm_phase(LAS unsigned char* lds, const Gemm g, const Sched& S, const Epi& E) {
;     ...
;             const bool last = (t == nt - 2);
;             const char* a1 = cA + (size_t)(t + 1) * kstep;
;             const char* a2 = last ? nA : cA + (size_t)(t + 2) * kstep; const char* b2 = last ? nB : cB + (size_t)(t + 2) * kstep;
;             const char* a3 = a2 + kstep; const char* b3 = b2 + kstep;
;             PG8_LDB(B0, 0, 0); PG8_SCHED; PG8_LDA(At, 0, 0); PG8_STAGE(PG8_SA(1, 1), a1 + hstep, voffA);
;             PG8_WAIT_L(8); PG8_BAR; PG8_WAIT_L(0); PG8_MMA(0, 0, At, B0); PG8_BAR; PG8_SCHED;
;             PG8_LDB(B1, 0, 1); PG8_STAGE(PG8_SB(0, 0), b2, voffB);
;             PG8_BAR; PG8_WAIT_L(0); PG8_MMA(0, 1, At, B1); PG8_BAR;
;             PG8_LDA(At, 0, 1); PG8_STAGE(PG8_SA(0, 0), a2, voffA);
;             PG8_BAR; PG8_WAIT_L(0); PG8_MMA(1, 0, At, B0); PG8_BAR; PG8_SCHED;
;             PG8_STAGE(PG8_SB(0, 1), b2 + hstep, voffB);
;             PG8_WAIT_V(6); PG8_BAR; PG8_MMA(1, 1, At, B1); PG8_BAR;
.LBB0_557:
	s_add_u32 s24, s0, 0xfffc0080
	s_addc_u32 s25, s1, -1
	s_add_i32 s39, 0, 0x10000
	v_add_u32_e32 v162, s39, v164
	s_cmp_eq_u32 s38, 12
	s_cselect_b32 vcc_hi, s77, s25
	s_cselect_b32 vcc_lo, s76, s24
	s_cselect_b32 s49, s45, s50
	s_cselect_b32 s48, s47, s35
	s_add_i32 m0, s95, 0xc000
	ds_read_b128 v[218:221], v166 offset:6144
	ds_read_b128 v[222:225], v166 offset:7168
	global_load_lds_dwordx4 v140, s[0:1]
	s_add_i32 m0, s95, 0xe000
	s_nop 0
	global_load_lds_dwordx4 v138, s[0:1]
	s_waitcnt lgkmcnt(8)
	s_barrier
	s_waitcnt lgkmcnt(0)
	s_setprio 1
	s_waitcnt lgkmcnt(0)
	v_mfma_f32_16x16x32_bf16 v[126:129], v[142:145], v[194:197], v[126:129]
	v_mfma_f32_16x16x32_bf16 v[126:129], v[182:185], v[198:201], v[126:129]
	v_mfma_f32_16x16x32_bf16 v[122:125], v[186:189], v[194:197], v[122:125]
	v_mfma_f32_16x16x32_bf16 v[122:125], v[190:193], v[198:201], v[122:125]
	v_mfma_f32_16x16x32_bf16 v[110:113], v[142:145], v[202:205], v[110:113]
	v_mfma_f32_16x16x32_bf16 v[110:113], v[182:185], v[206:209], v[110:113]
	v_mfma_f32_16x16x32_bf16 v[106:109], v[186:189], v[202:205], v[106:109]
	v_mfma_f32_16x16x32_bf16 v[106:109], v[190:193], v[206:209], v[106:109]
	v_mfma_f32_16x16x32_bf16 v[94:97], v[142:145], v[210:213], v[94:97]
	v_mfma_f32_16x16x32_bf16 v[94:97], v[182:185], v[214:217], v[94:97]
	v_mfma_f32_16x16x32_bf16 v[90:93], v[186:189], v[210:213], v[90:93]
	v_mfma_f32_16x16x32_bf16 v[90:93], v[190:193], v[214:217], v[90:93]
	v_mfma_f32_16x16x32_bf16 v[78:81], v[142:145], v[218:221], v[78:81]
	v_mfma_f32_16x16x32_bf16 v[78:81], v[182:185], v[222:225], v[78:81]
	v_mfma_f32_16x16x32_bf16 v[74:77], v[186:189], v[218:221], v[74:77]
	s_barrier
	v_mfma_f32_16x16x32_bf16 v[74:77], v[190:193], v[222:225], v[74:77]
	s_setprio 0
	s_add_i32 s51, 0, 0x14000
	v_add_u32_e32 v162, s51, v164
	s_add_i32 s24, s39, s94
	ds_read_b128 v[226:229], v162
	ds_read_b128 v[230:233], v162 offset:1024
	ds_read_b128 v[234:237], v162 offset:2048
	ds_read_b128 v[238:241], v162 offset:3072
	v_lshl_add_u64 v[162:163], s[48:49], 0, v[134:135]
	s_mov_b32 m0, s24
	v_lshl_add_u64 v[168:169], s[48:49], 0, v[130:131]
	global_load_lds_dwordx4 v[162:163], off
	s_add_i32 m0, s24, 0x2000
	s_nop 0
	global_load_lds_dwordx4 v[168:169], off
	s_barrier
	s_waitcnt lgkmcnt(0)
	s_setprio 1
	s_waitcnt lgkmcnt(0)
	v_mfma_f32_16x16x32_bf16 v[118:121], v[226:229], v[194:197], v[118:121]
	v_mfma_f32_16x16x32_bf16 v[118:121], v[230:233], v[198:201], v[118:121]
	v_mfma_f32_16x16x32_bf16 v[114:117], v[234:237], v[194:197], v[114:117]
	v_mfma_f32_16x16x32_bf16 v[114:117], v[238:241], v[198:201], v[114:117]
	v_mfma_f32_16x16x32_bf16 v[102:105], v[226:229], v[202:205], v[102:105]
	v_mfma_f32_16x16x32_bf16 v[102:105], v[230:233], v[206:209], v[102:105]
	v_mfma_f32_16x16x32_bf16 v[98:101], v[234:237], v[202:205], v[98:101]
	v_mfma_f32_16x16x32_bf16 v[98:101], v[238:241], v[206:209], v[98:101]
	v_mfma_f32_16x16x32_bf16 v[86:89], v[226:229], v[210:213], v[86:89]
	v_mfma_f32_16x16x32_bf16 v[86:89], v[230:233], v[214:217], v[86:89]
	v_mfma_f32_16x16x32_bf16 v[82:85], v[234:237], v[210:213], v[82:85]
	v_mfma_f32_16x16x32_bf16 v[82:85], v[238:241], v[214:217], v[82:85]
	v_mfma_f32_16x16x32_bf16 v[70:73], v[226:229], v[218:221], v[70:73]
	v_mfma_f32_16x16x32_bf16 v[70:73], v[230:233], v[222:225], v[70:73]
	v_mfma_f32_16x16x32_bf16 v[66:69], v[234:237], v[218:221], v[66:69]
	s_barrier
	v_mfma_f32_16x16x32_bf16 v[66:69], v[238:241], v[222:225], v[66:69]
	s_setprio 0
	s_mov_b32 m0, s95
	v_lshl_add_u64 v[242:243], vcc, 0, v[136:137]
	ds_read_b128 v[194:197], v166 offset:16384
	ds_read_b128 v[198:201], v166 offset:17408
	ds_read_b128 v[202:205], v166 offset:18432
	ds_read_b128 v[206:209], v166 offset:19456
	ds_read_b128 v[210:213], v166 offset:20480
	ds_read_b128 v[214:217], v166 offset:21504
	ds_read_b128 v[218:221], v166 offset:22528
	ds_read_b128 v[222:225], v166 offset:23552
	global_load_lds_dwordx4 v[242:243], off
	v_lshl_add_u64 v[244:245], vcc, 0, v[132:133]
	s_mov_b32 m0, s96
	s_nop 0
	global_load_lds_dwordx4 v[244:245], off
	s_waitcnt vmcnt(8)
	s_barrier
	s_waitcnt lgkmcnt(0)
	s_setprio 1
	s_waitcnt lgkmcnt(0)
	v_mfma_f32_16x16x32_bf16 v[62:65], v[142:145], v[194:197], v[62:65]
	v_mfma_f32_16x16x32_bf16 v[62:65], v[182:185], v[198:201], v[62:65]
	v_mfma_f32_16x16x32_bf16 v[58:61], v[186:189], v[194:197], v[58:61]
	v_mfma_f32_16x16x32_bf16 v[58:61], v[190:193], v[198:201], v[58:61]
	v_mfma_f32_16x16x32_bf16 v[46:49], v[142:145], v[202:205], v[46:49]
	v_mfma_f32_16x16x32_bf16 v[46:49], v[182:185], v[206:209], v[46:49]
	v_mfma_f32_16x16x32_bf16 v[42:45], v[186:189], v[202:205], v[42:45]
	v_mfma_f32_16x16x32_bf16 v[42:45], v[190:193], v[206:209], v[42:45]
	v_mfma_f32_16x16x32_bf16 v[30:33], v[142:145], v[210:213], v[30:33]
	v_mfma_f32_16x16x32_bf16 v[30:33], v[182:185], v[214:217], v[30:33]
	v_mfma_f32_16x16x32_bf16 v[26:29], v[186:189], v[210:213], v[26:29]
	v_mfma_f32_16x16x32_bf16 v[26:29], v[190:193], v[214:217], v[26:29]
	v_mfma_f32_16x16x32_bf16 v[14:17], v[142:145], v[218:221], v[14:17]
	v_mfma_f32_16x16x32_bf16 v[14:17], v[182:185], v[222:225], v[14:17]
	v_mfma_f32_16x16x32_bf16 v[10:13], v[186:189], v[218:221], v[10:13]
	s_barrier
	v_mfma_f32_16x16x32_bf16 v[10:13], v[190:193], v[222:225], v[10:13]
	s_setprio 0
	s_add_u32 s24, s48, 0x40000
	s_addc_u32 s25, s49, 0
	s_add_i32 s39, s51, s94
	s_mov_b32 m0, s39
	s_nop 0
	global_load_lds_dwordx4 v134, s[24:25]
	s_add_i32 m0, s39, 0x2000
	s_nop 0
	global_load_lds_dwordx4 v130, s[24:25]
	s_waitcnt vmcnt(6)
	s_barrier
; #define PG8_STAGE(bufoff, gbase, voff) do { _Pragma("unroll") for (int _i = 0; _i < 2; ++_i) \
;         __builtin_amdgcn_global_load_lds((const unsigned*)((const char*)(gbase) + (voff)[_i]), (LAS unsigned*)(lds + (bufoff) + ldsw + _i * 8192), 16, 0, 0); } while (0)
; #define PG8_LDA(dst, b, h) do { _Pragma("unroll") for (int m = 0; m < 4; ++m) _Pragma("unroll") for (int k = 0; k < 2; ++k) dst[m][k] = *(const LAS bf16x8*)(lds + PG8_SA(b, h) + aoff + m * 2048 + k * 1024); } while (0)
; #define PG8_LDB(dst, b, h) do { _Pragma("unroll") for (int n = 0; n < 2; ++n) _Pragma("unroll") for (int k = 0; k < 2; ++k) dst[n][k] = *(const LAS bf16x8*)(lds + PG8_SB(b, h) + boff + n * 2048 + k * 1024); } while (0)
; #define PG8_MMA(ai, bj, At, Bt) do { __builtin_amdgcn_s_setprio(1); _Pragma("unroll") for (int m = 0; m < 4; ++m) _Pragma("unroll") for (int n = 0; n < 2; ++n) _Pragma("unroll") for (int k = 0; k < 2; ++k) \
;         acc[ai][bj][m][n] = __builtin_amdgcn_mfma_f32_16x16x32_bf16(Bt[n][k], At[m][k], acc[ai][bj][m][n], 0, 0, 0); __builtin_amdgcn_s_setprio(0); } while (0)
; #define PG8_WAIT_V(n) asm volatile("s_waitcnt vmcnt(" #n ")" ::: "memory")
; #define PG8_WAIT_L(n) asm volatile("s_waitcnt lgkmcnt(" #n ")" ::: "memory")
; #define PG8_BAR __builtin_amdgcn_s_barrier()
; #define PG8_SCHED __builtin_amdgcn_sched_barrier(0)
; template <class Epi, class Sched>
; __device__ __forceinline__ void gemm_phase(LAS unsigned char* lds, const Gemm g, const Sched& S, const Epi& E) {
;     ...
;             PG8_WAIT_V(6); PG8_BAR; PG8_MMA(1, 1, At, B1); PG8_BAR;
;             PG8_LDB(B0, 1, 0); PG8_SCHED; PG8_LDA(At, 1, 0); PG8_STAGE(PG8_SA(0, 1), a2 + hstep, voffA);
;             PG8_WAIT_L(8); PG8_BAR; PG8_WAIT_L(0); PG8_MMA(0, 0, At, B0); PG8_BAR; PG8_SCHED;
;             PG8_LDB(B1, 1, 1); PG8_STAGE(PG8_SB(1, 0), b3, voffB);
;             PG8_BAR; PG8_WAIT_L(0); PG8_MMA(0, 1, At, B1); PG8_BAR;
	s_setprio 1
	v_add_u32_e32 v249, 0x18000, v164
	v_mfma_f32_16x16x32_bf16 v[54:57], v[226:229], v[194:197], v[54:57]
	ds_read_b128 v[142:145], v249
	ds_read_b128 v[182:185], v249 offset:1024
	v_mfma_f32_16x16x32_bf16 v[54:57], v[230:233], v[198:201], v[54:57]
	ds_read_b128 v[186:189], v249 offset:2048
	ds_read_b128 v[190:193], v249 offset:3072
	v_mfma_f32_16x16x32_bf16 v[50:53], v[234:237], v[194:197], v[50:53]
	ds_read_b128 v[194:197], v166 offset:32768
	v_mfma_f32_16x16x32_bf16 v[50:53], v[238:241], v[198:201], v[50:53]
	ds_read_b128 v[198:201], v166 offset:33792
	v_mfma_f32_16x16x32_bf16 v[38:41], v[226:229], v[202:205], v[38:41]
	v_mfma_f32_16x16x32_bf16 v[38:41], v[230:233], v[206:209], v[38:41]
	v_mfma_f32_16x16x32_bf16 v[34:37], v[234:237], v[202:205], v[34:37]
	ds_read_b128 v[202:205], v166 offset:34816
	v_mfma_f32_16x16x32_bf16 v[34:37], v[238:241], v[206:209], v[34:37]
	ds_read_b128 v[206:209], v166 offset:35840
	v_mfma_f32_16x16x32_bf16 v[22:25], v[226:229], v[210:213], v[22:25]
	v_mfma_f32_16x16x32_bf16 v[22:25], v[230:233], v[214:217], v[22:25]
	v_mfma_f32_16x16x32_bf16 v[18:21], v[234:237], v[210:213], v[18:21]
	ds_read_b128 v[210:213], v166 offset:36864
	v_mfma_f32_16x16x32_bf16 v[18:21], v[238:241], v[214:217], v[18:21]
	ds_read_b128 v[214:217], v166 offset:37888
	v_mfma_f32_16x16x32_bf16 v[6:9], v[226:229], v[218:221], v[6:9]
	v_mfma_f32_16x16x32_bf16 v[6:9], v[230:233], v[222:225], v[6:9]
	v_mfma_f32_16x16x32_bf16 v[2:5], v[234:237], v[218:221], v[2:5]
	s_barrier
	v_mfma_f32_16x16x32_bf16 v[2:5], v[238:241], v[222:225], v[2:5]
	s_setprio 0
	s_add_i32 s39, 0, 0x18000
	v_add_u32_e32 v167, s39, v164
	s_add_u32 s24, vcc_lo, 0x40000
	s_addc_u32 s25, vcc_hi, 0
	s_mov_b32 m0, s97
	ds_read_b128 v[218:221], v166 offset:38912
	ds_read_b128 v[222:225], v166 offset:39936
	global_load_lds_dwordx4 v136, s[24:25]
	s_mov_b32 m0, s98
	s_nop 0
	global_load_lds_dwordx4 v132, s[24:25]
	s_waitcnt lgkmcnt(8)
	s_barrier
	s_waitcnt lgkmcnt(0)
	s_setprio 1
	s_waitcnt lgkmcnt(0)
	v_mfma_f32_16x16x32_bf16 v[126:129], v[142:145], v[194:197], v[126:129]
	v_mfma_f32_16x16x32_bf16 v[126:129], v[182:185], v[198:201], v[126:129]
	v_mfma_f32_16x16x32_bf16 v[122:125], v[186:189], v[194:197], v[122:125]
	v_mfma_f32_16x16x32_bf16 v[122:125], v[190:193], v[198:201], v[122:125]
	v_mfma_f32_16x16x32_bf16 v[110:113], v[142:145], v[202:205], v[110:113]
	v_mfma_f32_16x16x32_bf16 v[110:113], v[182:185], v[206:209], v[110:113]
	v_mfma_f32_16x16x32_bf16 v[106:109], v[186:189], v[202:205], v[106:109]
	v_mfma_f32_16x16x32_bf16 v[106:109], v[190:193], v[206:209], v[106:109]
	v_mfma_f32_16x16x32_bf16 v[94:97], v[142:145], v[210:213], v[94:97]
	v_mfma_f32_16x16x32_bf16 v[94:97], v[182:185], v[214:217], v[94:97]
	v_mfma_f32_16x16x32_bf16 v[90:93], v[186:189], v[210:213], v[90:93]
	v_mfma_f32_16x16x32_bf16 v[90:93], v[190:193], v[214:217], v[90:93]
	v_mfma_f32_16x16x32_bf16 v[78:81], v[142:145], v[218:221], v[78:81]
	v_mfma_f32_16x16x32_bf16 v[78:81], v[182:185], v[222:225], v[78:81]
	v_mfma_f32_16x16x32_bf16 v[74:77], v[186:189], v[218:221], v[74:77]
	s_barrier
	v_mfma_f32_16x16x32_bf16 v[74:77], v[190:193], v[222:225], v[74:77]
	s_setprio 0
	s_add_i32 s51, 0, 0x1c000
	s_add_i32 s24, s39, s94
	v_add_u32_e32 v167, s51, v164
	v_lshl_add_u64 v[162:163], v[162:163], 0, s[12:13]
	s_mov_b32 m0, s24
	ds_read_b128 v[226:229], v167
	ds_read_b128 v[230:233], v167 offset:1024
	ds_read_b128 v[234:237], v167 offset:2048
	ds_read_b128 v[238:241], v167 offset:3072
	global_load_lds_dwordx4 v[162:163], off
	v_lshl_add_u64 v[250:251], v[168:169], 0, s[12:13]
	s_add_i32 m0, s24, 0x2000
	s_nop 0
	global_load_lds_dwordx4 v[250:251], off
	s_barrier
	s_waitcnt lgkmcnt(0)
	s_setprio 1
	s_waitcnt lgkmcnt(0)
	v_mfma_f32_16x16x32_bf16 v[118:121], v[226:229], v[194:197], v[118:121]
	v_mfma_f32_16x16x32_bf16 v[118:121], v[230:233], v[198:201], v[118:121]
	v_mfma_f32_16x16x32_bf16 v[114:117], v[234:237], v[194:197], v[114:117]
	v_mfma_f32_16x16x32_bf16 v[114:117], v[238:241], v[198:201], v[114:117]
	v_mfma_f32_16x16x32_bf16 v[102:105], v[226:229], v[202:205], v[102:105]
	v_mfma_f32_16x16x32_bf16 v[102:105], v[230:233], v[206:209], v[102:105]
	v_mfma_f32_16x16x32_bf16 v[98:101], v[234:237], v[202:205], v[98:101]
	v_mfma_f32_16x16x32_bf16 v[98:101], v[238:241], v[206:209], v[98:101]
	v_mfma_f32_16x16x32_bf16 v[86:89], v[226:229], v[210:213], v[86:89]
	v_mfma_f32_16x16x32_bf16 v[86:89], v[230:233], v[214:217], v[86:89]
	v_mfma_f32_16x16x32_bf16 v[82:85], v[234:237], v[210:213], v[82:85]
	v_mfma_f32_16x16x32_bf16 v[82:85], v[238:241], v[214:217], v[82:85]
	v_mfma_f32_16x16x32_bf16 v[70:73], v[226:229], v[218:221], v[70:73]
	v_mfma_f32_16x16x32_bf16 v[70:73], v[230:233], v[222:225], v[70:73]
	v_mfma_f32_16x16x32_bf16 v[66:69], v[234:237], v[218:221], v[66:69]
	s_barrier
; #define PG8_STAGE(bufoff, gbase, voff) do { _Pragma("unroll") for (int _i = 0; _i < 2; ++_i) \
;         __builtin_amdgcn_global_load_lds((const unsigned*)((const char*)(gbase) + (voff)[_i]), (LAS unsigned*)(lds + (bufoff) + ldsw + _i * 8192), 16, 0, 0); } while (0)
; #define PG8_LDA(dst, b, h) do { _Pragma("unroll") for (int m = 0; m < 4; ++m) _Pragma("unroll") for (int k = 0; k < 2; ++k) dst[m][k] = *(const LAS bf16x8*)(lds + PG8_SA(b, h) + aoff + m * 2048 + k * 1024); } while (0)
; #define PG8_MMA(ai, bj, At, Bt) do { __builtin_amdgcn_s_setprio(1); _Pragma("unroll") for (int m = 0; m < 4; ++m) _Pragma("unroll") for (int n = 0; n < 2; ++n) _Pragma("unroll") for (int k = 0; k < 2; ++k) \
;         acc[ai][bj][m][n] = __builtin_amdgcn_mfma_f32_16x16x32_bf16(Bt[n][k], At[m][k], acc[ai][bj][m][n], 0, 0, 0); __builtin_amdgcn_s_setprio(0); } while (0)
; #define PG8_WAIT_V(n) asm volatile("s_waitcnt vmcnt(" #n ")" ::: "memory")
; #define PG8_WAIT_L(n) asm volatile("s_waitcnt lgkmcnt(" #n ")" ::: "memory")
; #define PG8_BAR __builtin_amdgcn_s_barrier()
; #define PG8_SCHED __builtin_amdgcn_sched_barrier(0)
; template <class Epi, class Sched>
; __device__ __forceinline__ void gemm_phase(LAS unsigned char* lds, const Gemm g, const Sched& S, const Epi& E) {
;     ...
;             PG8_LDA(At, 1, 1); PG8_STAGE(PG8_SA(1, 0), a3, voffA);
;             PG8_BAR; PG8_WAIT_L(0); PG8_MMA(1, 0, At, B0); PG8_BAR; PG8_SCHED;
;             PG8_STAGE(PG8_SB(1, 1), b3 + hstep, voffB);
;             PG8_WAIT_V(6); PG8_BAR; PG8_MMA(1, 1, At, B1); PG8_BAR;
;         }
	v_mfma_f32_16x16x32_bf16 v[66:69], v[238:241], v[222:225], v[66:69]
	s_setprio 0
	s_mov_b32 m0, s99
	v_lshl_add_u64 v[162:163], v[242:243], 0, s[12:13]
	ds_read_b128 v[194:197], v166 offset:49152
	ds_read_b128 v[198:201], v166 offset:50176
	ds_read_b128 v[202:205], v166 offset:51200
	ds_read_b128 v[206:209], v166 offset:52224
	ds_read_b128 v[210:213], v166 offset:53248
	ds_read_b128 v[214:217], v166 offset:54272
	ds_read_b128 v[218:221], v166 offset:55296
	ds_read_b128 v[222:225], v166 offset:56320
	global_load_lds_dwordx4 v[162:163], off
	v_lshl_add_u64 v[250:251], v[244:245], 0, s[12:13]
	s_mov_b32 m0, s82
	s_nop 0
	global_load_lds_dwordx4 v[250:251], off
	s_waitcnt vmcnt(8)
	s_barrier
	s_waitcnt lgkmcnt(0)
	s_setprio 1
	s_waitcnt lgkmcnt(0)
	v_mfma_f32_16x16x32_bf16 v[62:65], v[142:145], v[194:197], v[62:65]
	v_mfma_f32_16x16x32_bf16 v[62:65], v[182:185], v[198:201], v[62:65]
	v_mfma_f32_16x16x32_bf16 v[58:61], v[186:189], v[194:197], v[58:61]
	v_mfma_f32_16x16x32_bf16 v[58:61], v[190:193], v[198:201], v[58:61]
	v_mfma_f32_16x16x32_bf16 v[46:49], v[142:145], v[202:205], v[46:49]
	v_mfma_f32_16x16x32_bf16 v[46:49], v[182:185], v[206:209], v[46:49]
	v_mfma_f32_16x16x32_bf16 v[42:45], v[186:189], v[202:205], v[42:45]
	v_mfma_f32_16x16x32_bf16 v[42:45], v[190:193], v[206:209], v[42:45]
	v_mfma_f32_16x16x32_bf16 v[30:33], v[142:145], v[210:213], v[30:33]
	v_mfma_f32_16x16x32_bf16 v[30:33], v[182:185], v[214:217], v[30:33]
	v_mfma_f32_16x16x32_bf16 v[26:29], v[186:189], v[210:213], v[26:29]
	v_mfma_f32_16x16x32_bf16 v[26:29], v[190:193], v[214:217], v[26:29]
	v_mfma_f32_16x16x32_bf16 v[14:17], v[142:145], v[218:221], v[14:17]
	v_mfma_f32_16x16x32_bf16 v[14:17], v[182:185], v[222:225], v[14:17]
	v_mfma_f32_16x16x32_bf16 v[10:13], v[186:189], v[218:221], v[10:13]
	s_barrier
	v_mfma_f32_16x16x32_bf16 v[10:13], v[190:193], v[222:225], v[10:13]
	s_setprio 0
	s_add_u32 s24, s48, 0x40080
	s_addc_u32 s25, s49, 0
	s_add_i32 s39, s51, s94
	s_mov_b32 m0, s39
	s_nop 0
	global_load_lds_dwordx4 v134, s[24:25]
	s_add_i32 m0, s39, 0x2000
	s_nop 0
	global_load_lds_dwordx4 v130, s[24:25]
	s_waitcnt vmcnt(6)
	s_barrier
	s_setprio 1
	v_add_u32_e32 v249, 0x10000, v164
	v_mfma_f32_16x16x32_bf16 v[54:57], v[226:229], v[194:197], v[54:57]
	ds_read_b128 v[142:145], v249
	ds_read_b128 v[182:185], v249 offset:1024
	v_mfma_f32_16x16x32_bf16 v[54:57], v[230:233], v[198:201], v[54:57]
	ds_read_b128 v[186:189], v249 offset:2048
	ds_read_b128 v[190:193], v249 offset:3072
	v_mfma_f32_16x16x32_bf16 v[50:53], v[234:237], v[194:197], v[50:53]
	ds_read_b128 v[194:197], v166
	v_mfma_f32_16x16x32_bf16 v[50:53], v[238:241], v[198:201], v[50:53]
	ds_read_b128 v[198:201], v166 offset:1024
	v_mfma_f32_16x16x32_bf16 v[38:41], v[226:229], v[202:205], v[38:41]
	v_mfma_f32_16x16x32_bf16 v[38:41], v[230:233], v[206:209], v[38:41]
	v_mfma_f32_16x16x32_bf16 v[34:37], v[234:237], v[202:205], v[34:37]
	ds_read_b128 v[202:205], v166 offset:2048
	v_mfma_f32_16x16x32_bf16 v[34:37], v[238:241], v[206:209], v[34:37]
	ds_read_b128 v[206:209], v166 offset:3072
	v_mfma_f32_16x16x32_bf16 v[22:25], v[226:229], v[210:213], v[22:25]
	v_mfma_f32_16x16x32_bf16 v[22:25], v[230:233], v[214:217], v[22:25]
	v_mfma_f32_16x16x32_bf16 v[18:21], v[234:237], v[210:213], v[18:21]
	ds_read_b128 v[210:213], v166 offset:4096
	v_mfma_f32_16x16x32_bf16 v[18:21], v[238:241], v[214:217], v[18:21]
	ds_read_b128 v[214:217], v166 offset:5120
	v_mfma_f32_16x16x32_bf16 v[6:9], v[226:229], v[218:221], v[6:9]
	v_mfma_f32_16x16x32_bf16 v[6:9], v[230:233], v[222:225], v[6:9]
	v_mfma_f32_16x16x32_bf16 v[2:5], v[234:237], v[218:221], v[2:5]
	s_barrier
	v_mfma_f32_16x16x32_bf16 v[2:5], v[238:241], v[222:225], v[2:5]
	s_setprio 0
	s_add_i32 s38, s38, 2
	s_add_u32 s35, s35, 0x100
	s_addc_u32 s50, s50, 0
	s_add_u32 s0, s0, 0x100
	s_addc_u32 s1, s1, 0
	s_cmp_gt_u32 s38, 13
	s_cbranch_scc0 .LBB0_557
	s_waitcnt lgkmcnt(0)
	s_and_b64 vcc, exec, s[42:43]
	s_cbranch_vccz .LBB0_560
	s_barrier

; #define PG8_STAGE(bufoff, gbase, voff) do { _Pragma("unroll") for (int _i = 0; _i < 2; ++_i) \
;         __builtin_amdgcn_global_load_lds((const unsigned*)((const char*)(gbase) + (voff)[_i]), (LAS unsigned*)(lds + (bufoff) + ldsw + _i * 8192), 16, 0, 0); } while (0)
; #define PG8_LDA(dst, b, h) do { _Pragma("unroll") for (int m = 0; m < 4; ++m) _Pragma("unroll") for (int k = 0; k < 2; ++k) dst[m][k] = *(const LAS bf16x8*)(lds + PG8_SA(b, h) + aoff + m * 2048 + k * 1024); } while (0)
; #define PG8_LDB(dst, b, h) do { _Pragma("unroll") for (int n = 0; n < 2; ++n) _Pragma("unroll") for (int k = 0; k < 2; ++k) dst[n][k] = *(const LAS bf16x8*)(lds + PG8_SB(b, h) + boff + n * 2048 + k * 1024); } while (0)
; #define PG8_MMA(ai, bj, At, Bt) do { __builtin_amdgcn_s_setprio(1); _Pragma("unroll") for (int m = 0; m < 4; ++m) _Pragma("unroll") for (int n = 0; n < 2; ++n) _Pragma("unroll") for (int k = 0; k < 2; ++k) \
;         acc[ai][bj][m][n] = __builtin_amdgcn_mfma_f32_16x16x32_bf16(Bt[n][k], At[m][k], acc[ai][bj][m][n], 0, 0, 0); __builtin_amdgcn_s_setprio(0); } while (0)
; #define PG8_WAIT_V(n) asm volatile("s_waitcnt vmcnt(" #n ")" ::: "memory")
; #define PG8_WAIT_L(n) asm volatile("s_waitcnt lgkmcnt(" #n ")" ::: "memory")
; #define PG8_BAR __builtin_amdgcn_s_barrier()
; template <class Epi, class Sched>
; __device__ __forceinline__ void gemm_phase(LAS unsigned char* lds, const Gemm g, const Sched& S, const Epi& E) {
;     ...
;             const bool last = (t == nt - 2);
;             const char* a1 = cA + (size_t)(t + 1) * kstep;
;             const char* a2 = last ? nA : cA + (size_t)(t + 2) * kstep; const char* b2 = last ? nB : cB + (size_t)(t + 2) * kstep;
;             const char* a3 = a2 + kstep; const char* b3 = b2 + kstep;
;             PG8_LDB(B0, 0, 0); PG8_SCHED; PG8_LDA(At, 0, 0); PG8_STAGE(PG8_SA(1, 1), a1 + hstep, voffA);
;             PG8_WAIT_L(8); PG8_BAR; PG8_WAIT_L(0); PG8_MMA(0, 0, At, B0); PG8_BAR; PG8_SCHED;
;             PG8_LDB(B1, 0, 1); PG8_STAGE(PG8_SB(0, 0), b2, voffB);
;             PG8_BAR; PG8_WAIT_L(0); PG8_MMA(0, 1, At, B1); PG8_BAR;
;             PG8_LDA(At, 0, 1); PG8_STAGE(PG8_SA(0, 0), a2, voffA);
;             PG8_BAR; PG8_WAIT_L(0); PG8_MMA(1, 0, At, B0); PG8_BAR; PG8_SCHED;
;             PG8_STAGE(PG8_SB(0, 1), b2 + hstep, voffB);
;             PG8_WAIT_V(6); PG8_BAR; PG8_MMA(1, 1, At, B1); PG8_BAR;
.LBB0_627:
	s_add_u32 s24, s0, 0xfff00080
	s_addc_u32 s25, s1, -1
	s_add_i32 s51, 0, 0x10000
	v_add_u32_e32 v142, s51, v144
	s_cmp_eq_u32 s98, 60
	s_cselect_b32 s77, s47, s25
	s_cselect_b32 s76, s46, s24
	s_cselect_b32 s49, s43, s50
	s_cselect_b32 s48, s45, s35
	s_add_i32 m0, s86, 0xc000
	ds_read_b128 v[218:221], v162 offset:6144
	ds_read_b128 v[222:225], v162 offset:7168
	global_load_lds_dwordx4 v140, s[0:1]
	s_add_i32 m0, s86, 0xe000
	s_nop 0
	global_load_lds_dwordx4 v138, s[0:1]
	s_waitcnt lgkmcnt(8)
	s_barrier
	s_waitcnt lgkmcnt(0)
	s_setprio 1
	s_waitcnt lgkmcnt(0)
	v_mfma_f32_16x16x32_bf16 v[126:129], v[164:167], v[194:197], v[126:129]
	v_mfma_f32_16x16x32_bf16 v[126:129], v[182:185], v[198:201], v[126:129]
	v_mfma_f32_16x16x32_bf16 v[122:125], v[186:189], v[194:197], v[122:125]
	v_mfma_f32_16x16x32_bf16 v[122:125], v[190:193], v[198:201], v[122:125]
	v_mfma_f32_16x16x32_bf16 v[118:121], v[164:167], v[202:205], v[118:121]
	v_mfma_f32_16x16x32_bf16 v[118:121], v[182:185], v[206:209], v[118:121]
	v_mfma_f32_16x16x32_bf16 v[110:113], v[186:189], v[202:205], v[110:113]
	v_mfma_f32_16x16x32_bf16 v[110:113], v[190:193], v[206:209], v[110:113]
	v_mfma_f32_16x16x32_bf16 v[102:105], v[164:167], v[210:213], v[102:105]
	v_mfma_f32_16x16x32_bf16 v[102:105], v[182:185], v[214:217], v[102:105]
	v_mfma_f32_16x16x32_bf16 v[94:97], v[186:189], v[210:213], v[94:97]
	v_mfma_f32_16x16x32_bf16 v[94:97], v[190:193], v[214:217], v[94:97]
	v_mfma_f32_16x16x32_bf16 v[86:89], v[164:167], v[218:221], v[86:89]
	v_mfma_f32_16x16x32_bf16 v[86:89], v[182:185], v[222:225], v[86:89]
	v_mfma_f32_16x16x32_bf16 v[78:81], v[186:189], v[218:221], v[78:81]
	s_barrier
	v_mfma_f32_16x16x32_bf16 v[78:81], v[190:193], v[222:225], v[78:81]
	s_setprio 0
	s_add_i32 s99, 0, 0x14000
	v_add_u32_e32 v142, s99, v144
	s_add_i32 s24, s51, s83
	ds_read_b128 v[226:229], v142
	ds_read_b128 v[230:233], v142 offset:1024
	ds_read_b128 v[234:237], v142 offset:2048
	ds_read_b128 v[238:241], v142 offset:3072
	v_lshl_add_u64 v[142:143], s[48:49], 0, v[134:135]
	s_mov_b32 m0, s24
	v_lshl_add_u64 v[168:169], s[48:49], 0, v[130:131]
	global_load_lds_dwordx4 v[142:143], off
	s_add_i32 m0, s24, 0x2000
	s_nop 0
	global_load_lds_dwordx4 v[168:169], off
	s_barrier
	s_waitcnt lgkmcnt(0)
	s_setprio 1
	s_waitcnt lgkmcnt(0)
	v_mfma_f32_16x16x32_bf16 v[114:117], v[226:229], v[194:197], v[114:117]
	v_mfma_f32_16x16x32_bf16 v[114:117], v[230:233], v[198:201], v[114:117]
	v_mfma_f32_16x16x32_bf16 v[106:109], v[234:237], v[194:197], v[106:109]
	v_mfma_f32_16x16x32_bf16 v[106:109], v[238:241], v[198:201], v[106:109]
	v_mfma_f32_16x16x32_bf16 v[98:101], v[226:229], v[202:205], v[98:101]
	v_mfma_f32_16x16x32_bf16 v[98:101], v[230:233], v[206:209], v[98:101]
	v_mfma_f32_16x16x32_bf16 v[90:93], v[234:237], v[202:205], v[90:93]
	v_mfma_f32_16x16x32_bf16 v[90:93], v[238:241], v[206:209], v[90:93]
	v_mfma_f32_16x16x32_bf16 v[82:85], v[226:229], v[210:213], v[82:85]
	v_mfma_f32_16x16x32_bf16 v[82:85], v[230:233], v[214:217], v[82:85]
	v_mfma_f32_16x16x32_bf16 v[74:77], v[234:237], v[210:213], v[74:77]
	v_mfma_f32_16x16x32_bf16 v[74:77], v[238:241], v[214:217], v[74:77]
	v_mfma_f32_16x16x32_bf16 v[70:73], v[226:229], v[218:221], v[70:73]
	v_mfma_f32_16x16x32_bf16 v[70:73], v[230:233], v[222:225], v[70:73]
	v_mfma_f32_16x16x32_bf16 v[66:69], v[234:237], v[218:221], v[66:69]
	s_barrier
	v_mfma_f32_16x16x32_bf16 v[66:69], v[238:241], v[222:225], v[66:69]
	s_setprio 0
	s_mov_b32 m0, s86
	v_lshl_add_u64 v[242:243], s[76:77], 0, v[136:137]
	ds_read_b128 v[194:197], v162 offset:16384
	ds_read_b128 v[198:201], v162 offset:17408
	ds_read_b128 v[202:205], v162 offset:18432
	ds_read_b128 v[206:209], v162 offset:19456
	ds_read_b128 v[210:213], v162 offset:20480
	ds_read_b128 v[214:217], v162 offset:21504
	ds_read_b128 v[218:221], v162 offset:22528
	ds_read_b128 v[222:225], v162 offset:23552
	global_load_lds_dwordx4 v[242:243], off
	v_lshl_add_u64 v[244:245], s[76:77], 0, v[132:133]
	s_mov_b32 m0, s92
	s_nop 0
	global_load_lds_dwordx4 v[244:245], off
	s_waitcnt vmcnt(8)
	s_barrier
	s_waitcnt lgkmcnt(0)
	s_setprio 1
	s_waitcnt lgkmcnt(0)
	v_mfma_f32_16x16x32_bf16 v[62:65], v[164:167], v[194:197], v[62:65]
	v_mfma_f32_16x16x32_bf16 v[62:65], v[182:185], v[198:201], v[62:65]
	v_mfma_f32_16x16x32_bf16 v[58:61], v[186:189], v[194:197], v[58:61]
	v_mfma_f32_16x16x32_bf16 v[58:61], v[190:193], v[198:201], v[58:61]
	v_mfma_f32_16x16x32_bf16 v[54:57], v[164:167], v[202:205], v[54:57]
	v_mfma_f32_16x16x32_bf16 v[54:57], v[182:185], v[206:209], v[54:57]
	v_mfma_f32_16x16x32_bf16 v[46:49], v[186:189], v[202:205], v[46:49]
	v_mfma_f32_16x16x32_bf16 v[46:49], v[190:193], v[206:209], v[46:49]
	v_mfma_f32_16x16x32_bf16 v[38:41], v[164:167], v[210:213], v[38:41]
	v_mfma_f32_16x16x32_bf16 v[38:41], v[182:185], v[214:217], v[38:41]
	v_mfma_f32_16x16x32_bf16 v[30:33], v[186:189], v[210:213], v[30:33]
	v_mfma_f32_16x16x32_bf16 v[30:33], v[190:193], v[214:217], v[30:33]
	v_mfma_f32_16x16x32_bf16 v[22:25], v[164:167], v[218:221], v[22:25]
	v_mfma_f32_16x16x32_bf16 v[22:25], v[182:185], v[222:225], v[22:25]
	v_mfma_f32_16x16x32_bf16 v[14:17], v[186:189], v[218:221], v[14:17]
	s_barrier
	v_mfma_f32_16x16x32_bf16 v[14:17], v[190:193], v[222:225], v[14:17]
	s_setprio 0
	s_add_u32 s24, s48, 0x100000
	s_addc_u32 s25, s49, 0
	s_add_i32 s51, s99, s83
	s_mov_b32 m0, s51
	s_nop 0
	global_load_lds_dwordx4 v134, s[24:25]
	s_add_i32 m0, s51, 0x2000
	s_nop 0
	global_load_lds_dwordx4 v130, s[24:25]
	s_waitcnt vmcnt(6)
	s_barrier
; #define PG8_STAGE(bufoff, gbase, voff) do { _Pragma("unroll") for (int _i = 0; _i < 2; ++_i) \
;         __builtin_amdgcn_global_load_lds((const unsigned*)((const char*)(gbase) + (voff)[_i]), (LAS unsigned*)(lds + (bufoff) + ldsw + _i * 8192), 16, 0, 0); } while (0)
; #define PG8_LDA(dst, b, h) do { _Pragma("unroll") for (int m = 0; m < 4; ++m) _Pragma("unroll") for (int k = 0; k < 2; ++k) dst[m][k] = *(const LAS bf16x8*)(lds + PG8_SA(b, h) + aoff + m * 2048 + k * 1024); } while (0)
; #define PG8_LDB(dst, b, h) do { _Pragma("unroll") for (int n = 0; n < 2; ++n) _Pragma("unroll") for (int k = 0; k < 2; ++k) dst[n][k] = *(const LAS bf16x8*)(lds + PG8_SB(b, h) + boff + n * 2048 + k * 1024); } while (0)
; #define PG8_MMA(ai, bj, At, Bt) do { __builtin_amdgcn_s_setprio(1); _Pragma("unroll") for (int m = 0; m < 4; ++m) _Pragma("unroll") for (int n = 0; n < 2; ++n) _Pragma("unroll") for (int k = 0; k < 2; ++k) \
;         acc[ai][bj][m][n] = __builtin_amdgcn_mfma_f32_16x16x32_bf16(Bt[n][k], At[m][k], acc[ai][bj][m][n], 0, 0, 0); __builtin_amdgcn_s_setprio(0); } while (0)
; #define PG8_WAIT_V(n) asm volatile("s_waitcnt vmcnt(" #n ")" ::: "memory")
; #define PG8_WAIT_L(n) asm volatile("s_waitcnt lgkmcnt(" #n ")" ::: "memory")
; #define PG8_BAR __builtin_amdgcn_s_barrier()
; #define PG8_SCHED __builtin_amdgcn_sched_barrier(0)
; template <class Epi, class Sched>
; __device__ __forceinline__ void gemm_phase(LAS unsigned char* lds, const Gemm g, const Sched& S, const Epi& E) {
;     ...
;             PG8_WAIT_V(6); PG8_BAR; PG8_MMA(1, 1, At, B1); PG8_BAR;
;             PG8_LDB(B0, 1, 0); PG8_SCHED; PG8_LDA(At, 1, 0); PG8_STAGE(PG8_SA(0, 1), a2 + hstep, voffA);
;             PG8_WAIT_L(8); PG8_BAR; PG8_WAIT_L(0); PG8_MMA(0, 0, At, B0); PG8_BAR; PG8_SCHED;
;             PG8_LDB(B1, 1, 1); PG8_STAGE(PG8_SB(1, 0), b3, voffB);
;             PG8_BAR; PG8_WAIT_L(0); PG8_MMA(0, 1, At, B1); PG8_BAR;
	s_setprio 1
	v_add_u32_e32 v249, 0x18000, v144
	v_mfma_f32_16x16x32_bf16 v[50:53], v[226:229], v[194:197], v[50:53]
	ds_read_b128 v[164:167], v249
	ds_read_b128 v[182:185], v249 offset:1024
	v_mfma_f32_16x16x32_bf16 v[50:53], v[230:233], v[198:201], v[50:53]
	ds_read_b128 v[186:189], v249 offset:2048
	ds_read_b128 v[190:193], v249 offset:3072
	v_mfma_f32_16x16x32_bf16 v[42:45], v[234:237], v[194:197], v[42:45]
	ds_read_b128 v[194:197], v162 offset:32768
	v_mfma_f32_16x16x32_bf16 v[42:45], v[238:241], v[198:201], v[42:45]
	ds_read_b128 v[198:201], v162 offset:33792
	v_mfma_f32_16x16x32_bf16 v[34:37], v[226:229], v[202:205], v[34:37]
	v_mfma_f32_16x16x32_bf16 v[34:37], v[230:233], v[206:209], v[34:37]
	v_mfma_f32_16x16x32_bf16 v[26:29], v[234:237], v[202:205], v[26:29]
	ds_read_b128 v[202:205], v162 offset:34816
	v_mfma_f32_16x16x32_bf16 v[26:29], v[238:241], v[206:209], v[26:29]
	ds_read_b128 v[206:209], v162 offset:35840
	v_mfma_f32_16x16x32_bf16 v[18:21], v[226:229], v[210:213], v[18:21]
	v_mfma_f32_16x16x32_bf16 v[18:21], v[230:233], v[214:217], v[18:21]
	v_mfma_f32_16x16x32_bf16 v[10:13], v[234:237], v[210:213], v[10:13]
	ds_read_b128 v[210:213], v162 offset:36864
	v_mfma_f32_16x16x32_bf16 v[10:13], v[238:241], v[214:217], v[10:13]
	ds_read_b128 v[214:217], v162 offset:37888
	v_mfma_f32_16x16x32_bf16 v[6:9], v[226:229], v[218:221], v[6:9]
	v_mfma_f32_16x16x32_bf16 v[6:9], v[230:233], v[222:225], v[6:9]
	v_mfma_f32_16x16x32_bf16 v[2:5], v[234:237], v[218:221], v[2:5]
	s_barrier
	v_mfma_f32_16x16x32_bf16 v[2:5], v[238:241], v[222:225], v[2:5]
	s_setprio 0
	s_add_i32 s51, 0, 0x18000
	v_add_u32_e32 v163, s51, v144
	s_add_u32 s24, s76, 0x100000
	s_addc_u32 s25, s77, 0
	s_mov_b32 m0, s93
	ds_read_b128 v[218:221], v162 offset:38912
	ds_read_b128 v[222:225], v162 offset:39936
	global_load_lds_dwordx4 v136, s[24:25]
	s_mov_b32 m0, s94
	s_nop 0
	global_load_lds_dwordx4 v132, s[24:25]
	s_waitcnt lgkmcnt(8)
	s_barrier
	s_waitcnt lgkmcnt(0)
	s_setprio 1
	s_waitcnt lgkmcnt(0)
	v_mfma_f32_16x16x32_bf16 v[126:129], v[164:167], v[194:197], v[126:129]
	v_mfma_f32_16x16x32_bf16 v[126:129], v[182:185], v[198:201], v[126:129]
	v_mfma_f32_16x16x32_bf16 v[122:125], v[186:189], v[194:197], v[122:125]
	v_mfma_f32_16x16x32_bf16 v[122:125], v[190:193], v[198:201], v[122:125]
	v_mfma_f32_16x16x32_bf16 v[118:121], v[164:167], v[202:205], v[118:121]
	v_mfma_f32_16x16x32_bf16 v[118:121], v[182:185], v[206:209], v[118:121]
	v_mfma_f32_16x16x32_bf16 v[110:113], v[186:189], v[202:205], v[110:113]
	v_mfma_f32_16x16x32_bf16 v[110:113], v[190:193], v[206:209], v[110:113]
	v_mfma_f32_16x16x32_bf16 v[102:105], v[164:167], v[210:213], v[102:105]
	v_mfma_f32_16x16x32_bf16 v[102:105], v[182:185], v[214:217], v[102:105]
	v_mfma_f32_16x16x32_bf16 v[94:97], v[186:189], v[210:213], v[94:97]
	v_mfma_f32_16x16x32_bf16 v[94:97], v[190:193], v[214:217], v[94:97]
	v_mfma_f32_16x16x32_bf16 v[86:89], v[164:167], v[218:221], v[86:89]
	v_mfma_f32_16x16x32_bf16 v[86:89], v[182:185], v[222:225], v[86:89]
	v_mfma_f32_16x16x32_bf16 v[78:81], v[186:189], v[218:221], v[78:81]
	s_barrier
	v_mfma_f32_16x16x32_bf16 v[78:81], v[190:193], v[222:225], v[78:81]
	s_setprio 0
	s_add_i32 s76, 0, 0x1c000
	s_add_i32 s24, s51, s83
	v_add_u32_e32 v163, s76, v144
	v_lshl_add_u64 v[142:143], v[142:143], 0, s[12:13]
	s_mov_b32 m0, s24
	ds_read_b128 v[226:229], v163
	ds_read_b128 v[230:233], v163 offset:1024
	ds_read_b128 v[234:237], v163 offset:2048
	ds_read_b128 v[238:241], v163 offset:3072
	global_load_lds_dwordx4 v[142:143], off
	v_lshl_add_u64 v[250:251], v[168:169], 0, s[12:13]
	s_add_i32 m0, s24, 0x2000
	s_nop 0
	global_load_lds_dwordx4 v[250:251], off
	s_barrier
	s_waitcnt lgkmcnt(0)
	s_setprio 1
	s_waitcnt lgkmcnt(0)
	v_mfma_f32_16x16x32_bf16 v[114:117], v[226:229], v[194:197], v[114:117]
	v_mfma_f32_16x16x32_bf16 v[114:117], v[230:233], v[198:201], v[114:117]
	v_mfma_f32_16x16x32_bf16 v[106:109], v[234:237], v[194:197], v[106:109]
	v_mfma_f32_16x16x32_bf16 v[106:109], v[238:241], v[198:201], v[106:109]
	v_mfma_f32_16x16x32_bf16 v[98:101], v[226:229], v[202:205], v[98:101]
	v_mfma_f32_16x16x32_bf16 v[98:101], v[230:233], v[206:209], v[98:101]
	v_mfma_f32_16x16x32_bf16 v[90:93], v[234:237], v[202:205], v[90:93]
	v_mfma_f32_16x16x32_bf16 v[90:93], v[238:241], v[206:209], v[90:93]
	v_mfma_f32_16x16x32_bf16 v[82:85], v[226:229], v[210:213], v[82:85]
	v_mfma_f32_16x16x32_bf16 v[82:85], v[230:233], v[214:217], v[82:85]
	v_mfma_f32_16x16x32_bf16 v[74:77], v[234:237], v[210:213], v[74:77]
	v_mfma_f32_16x16x32_bf16 v[74:77], v[238:241], v[214:217], v[74:77]
	v_mfma_f32_16x16x32_bf16 v[70:73], v[226:229], v[218:221], v[70:73]
	v_mfma_f32_16x16x32_bf16 v[70:73], v[230:233], v[222:225], v[70:73]
	v_mfma_f32_16x16x32_bf16 v[66:69], v[234:237], v[218:221], v[66:69]
	s_barrier
; #define PG8_STAGE(bufoff, gbase, voff) do { _Pragma("unroll") for (int _i = 0; _i < 2; ++_i) \
;         __builtin_amdgcn_global_load_lds((const unsigned*)((const char*)(gbase) + (voff)[_i]), (LAS unsigned*)(lds + (bufoff) + ldsw + _i * 8192), 16, 0, 0); } while (0)
; #define PG8_LDA(dst, b, h) do { _Pragma("unroll") for (int m = 0; m < 4; ++m) _Pragma("unroll") for (int k = 0; k < 2; ++k) dst[m][k] = *(const LAS bf16x8*)(lds + PG8_SA(b, h) + aoff + m * 2048 + k * 1024); } while (0)
; #define PG8_MMA(ai, bj, At, Bt) do { __builtin_amdgcn_s_setprio(1); _Pragma("unroll") for (int m = 0; m < 4; ++m) _Pragma("unroll") for (int n = 0; n < 2; ++n) _Pragma("unroll") for (int k = 0; k < 2; ++k) \
;         acc[ai][bj][m][n] = __builtin_amdgcn_mfma_f32_16x16x32_bf16(Bt[n][k], At[m][k], acc[ai][bj][m][n], 0, 0, 0); __builtin_amdgcn_s_setprio(0); } while (0)
; #define PG8_WAIT_V(n) asm volatile("s_waitcnt vmcnt(" #n ")" ::: "memory")
; #define PG8_WAIT_L(n) asm volatile("s_waitcnt lgkmcnt(" #n ")" ::: "memory")
; #define PG8_BAR __builtin_amdgcn_s_barrier()
; #define PG8_SCHED __builtin_amdgcn_sched_barrier(0)
; template <class Epi, class Sched>
; __device__ __forceinline__ void gemm_phase(LAS unsigned char* lds, const Gemm g, const Sched& S, const Epi& E) {
;     ...
;             PG8_LDA(At, 1, 1); PG8_STAGE(PG8_SA(1, 0), a3, voffA);
;             PG8_BAR; PG8_WAIT_L(0); PG8_MMA(1, 0, At, B0); PG8_BAR; PG8_SCHED;
;             PG8_STAGE(PG8_SB(1, 1), b3 + hstep, voffB);
;             PG8_WAIT_V(6); PG8_BAR; PG8_MMA(1, 1, At, B1); PG8_BAR;
;         }
	v_mfma_f32_16x16x32_bf16 v[66:69], v[238:241], v[222:225], v[66:69]
	s_setprio 0
	s_mov_b32 m0, s95
	v_lshl_add_u64 v[142:143], v[242:243], 0, s[12:13]
	ds_read_b128 v[194:197], v162 offset:49152
	ds_read_b128 v[198:201], v162 offset:50176
	ds_read_b128 v[202:205], v162 offset:51200
	ds_read_b128 v[206:209], v162 offset:52224
	ds_read_b128 v[210:213], v162 offset:53248
	ds_read_b128 v[214:217], v162 offset:54272
	ds_read_b128 v[218:221], v162 offset:55296
	ds_read_b128 v[222:225], v162 offset:56320
	global_load_lds_dwordx4 v[142:143], off
	v_lshl_add_u64 v[250:251], v[244:245], 0, s[12:13]
	s_mov_b32 m0, s96
	s_nop 0
	global_load_lds_dwordx4 v[250:251], off
	s_waitcnt vmcnt(8)
	s_barrier
	s_waitcnt lgkmcnt(0)
	s_setprio 1
	s_waitcnt lgkmcnt(0)
	v_mfma_f32_16x16x32_bf16 v[62:65], v[164:167], v[194:197], v[62:65]
	v_mfma_f32_16x16x32_bf16 v[62:65], v[182:185], v[198:201], v[62:65]
	v_mfma_f32_16x16x32_bf16 v[58:61], v[186:189], v[194:197], v[58:61]
	v_mfma_f32_16x16x32_bf16 v[58:61], v[190:193], v[198:201], v[58:61]
	v_mfma_f32_16x16x32_bf16 v[54:57], v[164:167], v[202:205], v[54:57]
	v_mfma_f32_16x16x32_bf16 v[54:57], v[182:185], v[206:209], v[54:57]
	v_mfma_f32_16x16x32_bf16 v[46:49], v[186:189], v[202:205], v[46:49]
	v_mfma_f32_16x16x32_bf16 v[46:49], v[190:193], v[206:209], v[46:49]
	v_mfma_f32_16x16x32_bf16 v[38:41], v[164:167], v[210:213], v[38:41]
	v_mfma_f32_16x16x32_bf16 v[38:41], v[182:185], v[214:217], v[38:41]
	v_mfma_f32_16x16x32_bf16 v[30:33], v[186:189], v[210:213], v[30:33]
	v_mfma_f32_16x16x32_bf16 v[30:33], v[190:193], v[214:217], v[30:33]
	v_mfma_f32_16x16x32_bf16 v[22:25], v[164:167], v[218:221], v[22:25]
	v_mfma_f32_16x16x32_bf16 v[22:25], v[182:185], v[222:225], v[22:25]
	v_mfma_f32_16x16x32_bf16 v[14:17], v[186:189], v[218:221], v[14:17]
	s_barrier
	v_mfma_f32_16x16x32_bf16 v[14:17], v[190:193], v[222:225], v[14:17]
	s_setprio 0
	s_add_u32 s24, s48, 0x100080
	s_addc_u32 s25, s49, 0
	s_add_i32 s48, s76, s83
	s_mov_b32 m0, s48
	s_nop 0
	global_load_lds_dwordx4 v134, s[24:25]
	s_add_i32 m0, s48, 0x2000
	s_nop 0
	global_load_lds_dwordx4 v130, s[24:25]
	s_waitcnt vmcnt(6)
	s_barrier
	s_setprio 1
	v_add_u32_e32 v249, 0x10000, v144
	v_mfma_f32_16x16x32_bf16 v[50:53], v[226:229], v[194:197], v[50:53]
	ds_read_b128 v[164:167], v249
	ds_read_b128 v[182:185], v249 offset:1024
	v_mfma_f32_16x16x32_bf16 v[50:53], v[230:233], v[198:201], v[50:53]
	ds_read_b128 v[186:189], v249 offset:2048
	ds_read_b128 v[190:193], v249 offset:3072
	v_mfma_f32_16x16x32_bf16 v[42:45], v[234:237], v[194:197], v[42:45]
	ds_read_b128 v[194:197], v162
	v_mfma_f32_16x16x32_bf16 v[42:45], v[238:241], v[198:201], v[42:45]
	ds_read_b128 v[198:201], v162 offset:1024
	v_mfma_f32_16x16x32_bf16 v[34:37], v[226:229], v[202:205], v[34:37]
	v_mfma_f32_16x16x32_bf16 v[34:37], v[230:233], v[206:209], v[34:37]
	v_mfma_f32_16x16x32_bf16 v[26:29], v[234:237], v[202:205], v[26:29]
	ds_read_b128 v[202:205], v162 offset:2048
	v_mfma_f32_16x16x32_bf16 v[26:29], v[238:241], v[206:209], v[26:29]
	ds_read_b128 v[206:209], v162 offset:3072
	v_mfma_f32_16x16x32_bf16 v[18:21], v[226:229], v[210:213], v[18:21]
	v_mfma_f32_16x16x32_bf16 v[18:21], v[230:233], v[214:217], v[18:21]
	v_mfma_f32_16x16x32_bf16 v[10:13], v[234:237], v[210:213], v[10:13]
	ds_read_b128 v[210:213], v162 offset:4096
	v_mfma_f32_16x16x32_bf16 v[10:13], v[238:241], v[214:217], v[10:13]
	ds_read_b128 v[214:217], v162 offset:5120
	v_mfma_f32_16x16x32_bf16 v[6:9], v[226:229], v[218:221], v[6:9]
	v_mfma_f32_16x16x32_bf16 v[6:9], v[230:233], v[222:225], v[6:9]
	v_mfma_f32_16x16x32_bf16 v[2:5], v[234:237], v[218:221], v[2:5]
	s_barrier
	v_mfma_f32_16x16x32_bf16 v[2:5], v[238:241], v[222:225], v[2:5]
	s_setprio 0
	s_add_i32 s98, s98, 2
	s_add_u32 s35, s35, 0x100
	s_addc_u32 s50, s50, 0
	s_add_u32 s0, s0, 0x100
	s_addc_u32 s1, s1, 0
	s_cmp_gt_u32 s98, 61
	s_cbranch_scc0 .LBB0_627
	s_waitcnt lgkmcnt(0)
	s_and_b64 vcc, exec, s[40:41]
	s_cbranch_vccz .LBB0_630
	s_barrier
